# sample-row GEMM blocks: DMA lanes remapped so 8 consecutive lanes fetch one 128-B row (XOR-swizzled chunk order keeps ds_read_b128 conflict-free)
# speedup vs baseline: 1.0675x; 1.0189x over previous
; template <class F>
; __device__ __forceinline__ void small_gemm_ks(LAS unsigned char* lds, const bf16_t* A, int lda, const bf16_t* Bt, int ldb, int K, int N, int a_grp_cols, int bx, int G, int tid, const F& f) {
;     const int lane = tid & 63, w = __builtin_amdgcn_readfirstlane(tid >> 6), c = lane & 15, g = lane >> 4, kh = w >> 2, wq = w & 3, wm = wq >> 1, wn = wq & 1;
;     const int ntn = N / 64, ntiles = (MS / 32) * ntn, KH = K / 2;
;     for (int t = bx; t < ntiles; t += G) {
;         const int row0 = MP + (t / ntn) * 32 + wm * 16, n0 = (t % ntn) * 64 + wn * 32;
;         const bf16_t* ap = A + (size_t)(row0 + c) * lda + (n0 >> 8) * a_grp_cols + kh * KH + 8 * g;
;         const bf16_t* bp = Bt + (size_t)(n0 + c) * ldb + kh * KH + 8 * g;
;         f32x4 acc[2] = {(f32x4){0.f, 0.f, 0.f, 0.f}, (f32x4){0.f, 0.f, 0.f, 0.f}};
; #pragma unroll 8
;         for (int k0 = 0; k0 < KH; k0 += 32) { const bf16x8 av = *(const bf16x8*)(ap + k0);
; #pragma unroll
;             for (int nt = 0; nt < 2; ++nt) { const bf16x8 bv = *(const bf16x8*)(bp + (size_t)nt * 16 * ldb + k0); acc[nt] = __builtin_amdgcn_mfma_f32_16x16x32_bf16(av, bv, acc[nt], 0, 0, 0); } }
.LBB0_886:
	s_waitcnt lgkmcnt(0)
	s_add_u32 s0, s6, 0xc80000
	s_addc_u32 s1, s7, 0
	s_add_u32 s3, s6, 0x9900000
	s_addc_u32 s4, s7, 0
	s_add_u32 s6, s6, 0x5700000
	s_addc_u32 s7, s7, 0
	v_readfirstlane_b32 s8, v20
	s_and_b64 vcc, exec, s[88:89]
	v_and_b32_e32 v14, 15, v20
	s_cbranch_vccnz .LBB0_893
	v_readfirstlane_b32 s68, v208
	v_and_b32_e32 v86, 63, v208
	s_nop 3
	s_lshr_b32 s68, s68, 6
	v_lshrrev_b32_e32 v87, 3, v86
	v_and_b32_e32 v88, 7, v86
	v_and_b32_e32 v94, 6, v87
	v_xor_b32_e32 v88, v88, v94
	s_mov_b32 s69, 5632
	v_mul_lo_u32 v90, v87, s69
	v_lshl_add_u32 v90, v88, 4, v90
	v_mov_b32_e32 v91, 0
	s_mov_b32 s69, 5632
	v_mul_lo_u32 v92, v87, s69
	v_lshl_add_u32 v92, v88, 4, v92
	v_mov_b32_e32 v93, 0
	v_and_b32_e32 v87, 15, v86
	v_lshrrev_b32_e32 v88, 4, v86
	v_lshrrev_b32_e32 v89, 3, v87
	v_lshlrev_b32_e32 v89, 10, v89
	v_and_b32_e32 v94, 6, v87
	v_xor_b32_e32 v94, v88, v94
	v_lshl_add_u32 v89, v94, 4, v89
	v_and_b32_e32 v94, 7, v87
	v_lshl_add_u32 v89, v94, 7, v89
	s_lshr_b32 s70, s68, 2
	s_bfe_u32 s71, s68, 0x10001
	s_and_b32 s72, s68, 1
	s_lshl_b32 s73, s70, 12
	s_lshl_b32 s74, s71, 11
	s_add_i32 s73, s73, s74
	s_lshl_b32 s74, s70, 13
	s_lshl_b32 s75, s72, 12
	s_add_i32 s74, s74, s75
	s_add_i32 s74, s74, 0x2000
	v_add_u32_e32 v96, s73, v89
	v_add_u32_e32 v101, s74, v89
	v_add_u32_e32 v97, s73, v89
	v_add_u32_e32 v102, s74, v89
	v_add_u32_e32 v98, s73, v89
	v_add_u32_e32 v103, s74, v89
	v_add_u32_e32 v99, s73, v89
	v_add_u32_e32 v104, s74, v89
	v_add_u32_e32 v100, s73, v89
	v_add_u32_e32 v105, s74, v89
	v_add_u32_e32 v97, 24576, v97
	v_add_u32_e32 v102, 24576, v102
	v_add_u32_e32 v98, 49152, v98
	v_add_u32_e32 v103, 49152, v103
	v_add_u32_e32 v99, 73728, v99
	v_add_u32_e32 v104, 73728, v104
	v_add_u32_e32 v100, 98304, v100
	v_add_u32_e32 v105, 98304, v105
	v_xor_b32_e32 v188, 64, v96
	v_xor_b32_e32 v193, 64, v101
	v_xor_b32_e32 v189, 64, v97
	v_xor_b32_e32 v194, 64, v102
	v_xor_b32_e32 v190, 64, v98
	v_xor_b32_e32 v195, 64, v103
	v_xor_b32_e32 v191, 64, v99
	v_xor_b32_e32 v196, 64, v104
	v_xor_b32_e32 v192, 64, v100
	v_xor_b32_e32 v197, 64, v105
	s_lshl_b32 s75, s71, 4
	v_lshl_add_u32 v106, v88, 2, s75
	v_lshlrev_b32_e32 v106, 11, v106
	s_lshl_b32 s75, s72, 5
	v_add_u32_e32 v107, s75, v87
	v_lshl_add_u32 v106, v107, 1, v106
	v_lshlrev_b32_e32 v108, 2, v107
	v_mov_b32_e32 v107, 0
	s_and_b32 s75, s68, 3
	s_lshl_b32 s75, s75, 11
	v_lshl_add_u32 v109, v86, 4, s75
	s_lshl_b32 s76, s68, 10
	s_lshl_b32 s77, s68, 11
	s_add_i32 s77, s77, 0x2000
	s_mov_b32 s78, 0x80
	s_mov_b32 s79, 0
	s_and_b32 s80, s68, 3
	s_mov_b32 s81, s2
.Lsg_dn0_tile:
	s_lshr_b32 s82, s81, 4
	s_and_b32 s83, s81, 15
	s_lshl_b32 s82, s82, 5
	s_add_i32 s82, s82, 0x4000
	s_lshl_b32 s83, s83, 6
	s_lshl_b32 s59, s80, 3
	s_add_i32 s59, s59, s82
	s_mul_i32 s60, s59, 5632
	s_mul_hi_u32 s61, s59, 5632
	s_mul_i32 s62, s70, 2816
	s_add_u32 s60, s60, s62
	s_addc_u32 s61, s61, 0
	s_add_u32 s60, s60, s54
	s_addc_u32 s61, s61, s55
	s_add_u32 s60, s60, 0x9900000
	s_addc_u32 s61, s61, 0
	v_lshl_add_u64 v[110:111], s[60:61], 0, v[90:91]
	s_lshl_b32 s59, s80, 4
	s_add_i32 s59, s59, s83
	s_mul_i32 s60, s59, 5632
	s_mul_i32 s62, s70, 2816
	s_add_u32 s60, s60, s62
	s_add_u32 s60, s60, s54
	s_addc_u32 s61, s55, 0
	s_add_u32 s60, s60, 0xc80000
	s_addc_u32 s61, s61, 0
	v_lshl_add_u64 v[112:113], s[60:61], 0, v[92:93]
	s_add_u32 s60, s60, 45056
	s_addc_u32 s61, s61, 0
	v_lshl_add_u64 v[114:115], s[60:61], 0, v[92:93]
	s_waitcnt vmcnt(0)
	v_mov_b32_e32 v120, 0
	v_mov_b32_e32 v121, 0
	v_mov_b32_e32 v122, 0
	v_mov_b32_e32 v123, 0
	v_mov_b32_e32 v124, 0
	v_mov_b32_e32 v125, 0
	v_mov_b32_e32 v126, 0
	v_mov_b32_e32 v127, 0
	s_add_i32 m0, s76, 0
	s_nop 0
	global_load_lds_dwordx4 v[110:111], off
	v_lshl_add_u64 v[110:111], v[110:111], 0, s[78:79]
	s_add_i32 m0, s77, 0
	s_nop 0
	global_load_lds_dwordx4 v[112:113], off
	v_lshl_add_u64 v[112:113], v[112:113], 0, s[78:79]
	s_add_i32 m0, s77, 1024
	s_nop 0
	global_load_lds_dwordx4 v[114:115], off
	v_lshl_add_u64 v[114:115], v[114:115], 0, s[78:79]
	s_add_i32 m0, s76, 24576
	s_nop 0
	global_load_lds_dwordx4 v[110:111], off
	v_lshl_add_u64 v[110:111], v[110:111], 0, s[78:79]
	s_add_i32 m0, s77, 24576
	s_nop 0
	global_load_lds_dwordx4 v[112:113], off
	v_lshl_add_u64 v[112:113], v[112:113], 0, s[78:79]
	s_add_i32 m0, s77, 25600
	s_nop 0
	global_load_lds_dwordx4 v[114:115], off
	v_lshl_add_u64 v[114:115], v[114:115], 0, s[78:79]
	s_add_i32 m0, s76, 49152
	s_nop 0
	global_load_lds_dwordx4 v[110:111], off
	v_lshl_add_u64 v[110:111], v[110:111], 0, s[78:79]
	s_add_i32 m0, s77, 49152
	s_nop 0
	global_load_lds_dwordx4 v[112:113], off
	v_lshl_add_u64 v[112:113], v[112:113], 0, s[78:79]
	s_add_i32 m0, s77, 50176
	s_nop 0
	global_load_lds_dwordx4 v[114:115], off
	v_lshl_add_u64 v[114:115], v[114:115], 0, s[78:79]
	s_add_i32 m0, s76, 73728
	s_nop 0
	global_load_lds_dwordx4 v[110:111], off
	v_lshl_add_u64 v[110:111], v[110:111], 0, s[78:79]
	s_add_i32 m0, s77, 73728
	s_nop 0
	global_load_lds_dwordx4 v[112:113], off
	v_lshl_add_u64 v[112:113], v[112:113], 0, s[78:79]
	s_add_i32 m0, s77, 74752
	s_nop 0
	global_load_lds_dwordx4 v[114:115], off
	v_lshl_add_u64 v[114:115], v[114:115], 0, s[78:79]
	s_waitcnt vmcnt(9)
	s_barrier
; template <class F>
; __device__ __forceinline__ void small_gemm_ks(LAS unsigned char* lds, const bf16_t* A, int lda, const bf16_t* Bt, int ldb, int K, int N, int a_grp_cols, int bx, int G, int tid, const F& f) {
;     ...
;         for (int k0 = 0; k0 < KH; k0 += 32) { const bf16x8 av = *(const bf16x8*)(ap + k0);
; #pragma unroll
;             for (int nt = 0; nt < 2; ++nt) { const bf16x8 bv = *(const bf16x8*)(bp + (size_t)nt * 16 * ldb + k0); acc[nt] = __builtin_amdgcn_mfma_f32_16x16x32_bf16(av, bv, acc[nt], 0, 0, 0); } }
	ds_read_b128 v[128:131], v96
	ds_read_b128 v[136:139], v101 offset:0
	ds_read_b128 v[144:147], v101 offset:2048
	ds_read_b128 v[132:135], v188
	ds_read_b128 v[140:143], v193 offset:0
	ds_read_b128 v[148:151], v193 offset:2048
	s_add_i32 m0, s76, 98304
	s_nop 0
	global_load_lds_dwordx4 v[110:111], off
	v_lshl_add_u64 v[110:111], v[110:111], 0, s[78:79]
	s_add_i32 m0, s77, 98304
	s_nop 0
	global_load_lds_dwordx4 v[112:113], off
	v_lshl_add_u64 v[112:113], v[112:113], 0, s[78:79]
	s_add_i32 m0, s77, 99328
	s_nop 0
	global_load_lds_dwordx4 v[114:115], off
	v_lshl_add_u64 v[114:115], v[114:115], 0, s[78:79]
	s_waitcnt lgkmcnt(3)
	v_mfma_f32_16x16x32_bf16 v[120:123], v[128:131], v[136:139], v[120:123]
	v_mfma_f32_16x16x32_bf16 v[124:127], v[128:131], v[144:147], v[124:127]
	s_waitcnt lgkmcnt(0)
	v_mfma_f32_16x16x32_bf16 v[120:123], v[132:135], v[140:143], v[120:123]
	v_mfma_f32_16x16x32_bf16 v[124:127], v[132:135], v[148:151], v[124:127]
	s_waitcnt vmcnt(9)
	s_barrier
	ds_read_b128 v[152:155], v97
	ds_read_b128 v[160:163], v102 offset:0
	ds_read_b128 v[168:171], v102 offset:2048
	ds_read_b128 v[156:159], v189
	ds_read_b128 v[164:167], v194 offset:0
	ds_read_b128 v[172:175], v194 offset:2048
	s_add_i32 m0, s76, 0
	s_nop 0
	global_load_lds_dwordx4 v[110:111], off
	v_lshl_add_u64 v[110:111], v[110:111], 0, s[78:79]
	s_add_i32 m0, s77, 0
	s_nop 0
	global_load_lds_dwordx4 v[112:113], off
	v_lshl_add_u64 v[112:113], v[112:113], 0, s[78:79]
	s_add_i32 m0, s77, 1024
	s_nop 0
	global_load_lds_dwordx4 v[114:115], off
	v_lshl_add_u64 v[114:115], v[114:115], 0, s[78:79]
	s_waitcnt lgkmcnt(3)
	v_mfma_f32_16x16x32_bf16 v[120:123], v[152:155], v[160:163], v[120:123]
	v_mfma_f32_16x16x32_bf16 v[124:127], v[152:155], v[168:171], v[124:127]
	s_waitcnt lgkmcnt(0)
	v_mfma_f32_16x16x32_bf16 v[120:123], v[156:159], v[164:167], v[120:123]
	v_mfma_f32_16x16x32_bf16 v[124:127], v[156:159], v[172:175], v[124:127]
	s_waitcnt vmcnt(9)
	s_barrier
	ds_read_b128 v[128:131], v98
	ds_read_b128 v[136:139], v103 offset:0
	ds_read_b128 v[144:147], v103 offset:2048
	ds_read_b128 v[132:135], v190
	ds_read_b128 v[140:143], v195 offset:0
	ds_read_b128 v[148:151], v195 offset:2048
	s_add_i32 m0, s76, 24576
	s_nop 0
	global_load_lds_dwordx4 v[110:111], off
	v_lshl_add_u64 v[110:111], v[110:111], 0, s[78:79]
	s_add_i32 m0, s77, 24576
	s_nop 0
	global_load_lds_dwordx4 v[112:113], off
	v_lshl_add_u64 v[112:113], v[112:113], 0, s[78:79]
	s_add_i32 m0, s77, 25600
	s_nop 0
	global_load_lds_dwordx4 v[114:115], off
	v_lshl_add_u64 v[114:115], v[114:115], 0, s[78:79]
	s_waitcnt lgkmcnt(3)
	v_mfma_f32_16x16x32_bf16 v[120:123], v[128:131], v[136:139], v[120:123]
	v_mfma_f32_16x16x32_bf16 v[124:127], v[128:131], v[144:147], v[124:127]
	s_waitcnt lgkmcnt(0)
	v_mfma_f32_16x16x32_bf16 v[120:123], v[132:135], v[140:143], v[120:123]
	v_mfma_f32_16x16x32_bf16 v[124:127], v[132:135], v[148:151], v[124:127]
	s_waitcnt vmcnt(9)
	s_barrier
	ds_read_b128 v[152:155], v99
	ds_read_b128 v[160:163], v104 offset:0
	ds_read_b128 v[168:171], v104 offset:2048
	ds_read_b128 v[156:159], v191
	ds_read_b128 v[164:167], v196 offset:0
	ds_read_b128 v[172:175], v196 offset:2048
	s_add_i32 m0, s76, 49152
	s_nop 0
	global_load_lds_dwordx4 v[110:111], off
	v_lshl_add_u64 v[110:111], v[110:111], 0, s[78:79]
	s_add_i32 m0, s77, 49152
	s_nop 0
	global_load_lds_dwordx4 v[112:113], off
	v_lshl_add_u64 v[112:113], v[112:113], 0, s[78:79]
	s_add_i32 m0, s77, 50176
	s_nop 0
	global_load_lds_dwordx4 v[114:115], off
	v_lshl_add_u64 v[114:115], v[114:115], 0, s[78:79]
	s_waitcnt lgkmcnt(3)
	v_mfma_f32_16x16x32_bf16 v[120:123], v[152:155], v[160:163], v[120:123]
	v_mfma_f32_16x16x32_bf16 v[124:127], v[152:155], v[168:171], v[124:127]
	s_waitcnt lgkmcnt(0)
	v_mfma_f32_16x16x32_bf16 v[120:123], v[156:159], v[164:167], v[120:123]
	v_mfma_f32_16x16x32_bf16 v[124:127], v[156:159], v[172:175], v[124:127]
	s_waitcnt vmcnt(9)
	s_barrier
	ds_read_b128 v[128:131], v100
	ds_read_b128 v[136:139], v105 offset:0
	ds_read_b128 v[144:147], v105 offset:2048
	ds_read_b128 v[132:135], v192
	ds_read_b128 v[140:143], v197 offset:0
	ds_read_b128 v[148:151], v197 offset:2048
	s_add_i32 m0, s76, 73728
	s_nop 0
	global_load_lds_dwordx4 v[110:111], off
	v_lshl_add_u64 v[110:111], v[110:111], 0, s[78:79]
	s_add_i32 m0, s77, 73728
	s_nop 0
	global_load_lds_dwordx4 v[112:113], off
	v_lshl_add_u64 v[112:113], v[112:113], 0, s[78:79]
	s_add_i32 m0, s77, 74752
	s_nop 0
	global_load_lds_dwordx4 v[114:115], off
	v_lshl_add_u64 v[114:115], v[114:115], 0, s[78:79]
	s_waitcnt lgkmcnt(3)
	v_mfma_f32_16x16x32_bf16 v[120:123], v[128:131], v[136:139], v[120:123]
	v_mfma_f32_16x16x32_bf16 v[124:127], v[128:131], v[144:147], v[124:127]
	s_waitcnt lgkmcnt(0)
	v_mfma_f32_16x16x32_bf16 v[120:123], v[132:135], v[140:143], v[120:123]
	v_mfma_f32_16x16x32_bf16 v[124:127], v[132:135], v[148:151], v[124:127]
	s_waitcnt vmcnt(9)
	s_barrier
	ds_read_b128 v[152:155], v96
	ds_read_b128 v[160:163], v101 offset:0
	ds_read_b128 v[168:171], v101 offset:2048
	ds_read_b128 v[156:159], v188
	ds_read_b128 v[164:167], v193 offset:0
	ds_read_b128 v[172:175], v193 offset:2048
	s_add_i32 m0, s76, 98304
	s_nop 0
	global_load_lds_dwordx4 v[110:111], off
	v_lshl_add_u64 v[110:111], v[110:111], 0, s[78:79]
	s_add_i32 m0, s77, 98304
	s_nop 0
	global_load_lds_dwordx4 v[112:113], off
	v_lshl_add_u64 v[112:113], v[112:113], 0, s[78:79]
	s_add_i32 m0, s77, 99328
	s_nop 0
	global_load_lds_dwordx4 v[114:115], off
	v_lshl_add_u64 v[114:115], v[114:115], 0, s[78:79]
	s_waitcnt lgkmcnt(3)
	v_mfma_f32_16x16x32_bf16 v[120:123], v[152:155], v[160:163], v[120:123]
	v_mfma_f32_16x16x32_bf16 v[124:127], v[152:155], v[168:171], v[124:127]
	s_waitcnt lgkmcnt(0)
	v_mfma_f32_16x16x32_bf16 v[120:123], v[156:159], v[164:167], v[120:123]
	v_mfma_f32_16x16x32_bf16 v[124:127], v[156:159], v[172:175], v[124:127]
	s_waitcnt vmcnt(9)
	s_barrier
; template <class F>
; __device__ __forceinline__ void small_gemm_ks(LAS unsigned char* lds, const bf16_t* A, int lda, const bf16_t* Bt, int ldb, int K, int N, int a_grp_cols, int bx, int G, int tid, const F& f) {
;     ...
;         for (int k0 = 0; k0 < KH; k0 += 32) { const bf16x8 av = *(const bf16x8*)(ap + k0);
; #pragma unroll
;             for (int nt = 0; nt < 2; ++nt) { const bf16x8 bv = *(const bf16x8*)(bp + (size_t)nt * 16 * ldb + k0); acc[nt] = __builtin_amdgcn_mfma_f32_16x16x32_bf16(av, bv, acc[nt], 0, 0, 0); } }
	ds_read_b128 v[128:131], v97
	ds_read_b128 v[136:139], v102 offset:0
	ds_read_b128 v[144:147], v102 offset:2048
	ds_read_b128 v[132:135], v189
	ds_read_b128 v[140:143], v194 offset:0
	ds_read_b128 v[148:151], v194 offset:2048
	s_add_i32 m0, s76, 0
	s_nop 0
	global_load_lds_dwordx4 v[110:111], off
	v_lshl_add_u64 v[110:111], v[110:111], 0, s[78:79]
	s_add_i32 m0, s77, 0
	s_nop 0
	global_load_lds_dwordx4 v[112:113], off
	v_lshl_add_u64 v[112:113], v[112:113], 0, s[78:79]
	s_add_i32 m0, s77, 1024
	s_nop 0
	global_load_lds_dwordx4 v[114:115], off
	v_lshl_add_u64 v[114:115], v[114:115], 0, s[78:79]
	s_waitcnt lgkmcnt(3)
	v_mfma_f32_16x16x32_bf16 v[120:123], v[128:131], v[136:139], v[120:123]
	v_mfma_f32_16x16x32_bf16 v[124:127], v[128:131], v[144:147], v[124:127]
	s_waitcnt lgkmcnt(0)
	v_mfma_f32_16x16x32_bf16 v[120:123], v[132:135], v[140:143], v[120:123]
	v_mfma_f32_16x16x32_bf16 v[124:127], v[132:135], v[148:151], v[124:127]
	s_waitcnt vmcnt(9)
	s_barrier
	ds_read_b128 v[152:155], v98
	ds_read_b128 v[160:163], v103 offset:0
	ds_read_b128 v[168:171], v103 offset:2048
	ds_read_b128 v[156:159], v190
	ds_read_b128 v[164:167], v195 offset:0
	ds_read_b128 v[172:175], v195 offset:2048
	s_add_i32 m0, s76, 24576
	s_nop 0
	global_load_lds_dwordx4 v[110:111], off
	v_lshl_add_u64 v[110:111], v[110:111], 0, s[78:79]
	s_add_i32 m0, s77, 24576
	s_nop 0
	global_load_lds_dwordx4 v[112:113], off
	v_lshl_add_u64 v[112:113], v[112:113], 0, s[78:79]
	s_add_i32 m0, s77, 25600
	s_nop 0
	global_load_lds_dwordx4 v[114:115], off
	v_lshl_add_u64 v[114:115], v[114:115], 0, s[78:79]
	s_waitcnt lgkmcnt(3)
	v_mfma_f32_16x16x32_bf16 v[120:123], v[152:155], v[160:163], v[120:123]
	v_mfma_f32_16x16x32_bf16 v[124:127], v[152:155], v[168:171], v[124:127]
	s_waitcnt lgkmcnt(0)
	v_mfma_f32_16x16x32_bf16 v[120:123], v[156:159], v[164:167], v[120:123]
	v_mfma_f32_16x16x32_bf16 v[124:127], v[156:159], v[172:175], v[124:127]
	s_waitcnt vmcnt(9)
	s_barrier
	ds_read_b128 v[128:131], v99
	ds_read_b128 v[136:139], v104 offset:0
	ds_read_b128 v[144:147], v104 offset:2048
	ds_read_b128 v[132:135], v191
	ds_read_b128 v[140:143], v196 offset:0
	ds_read_b128 v[148:151], v196 offset:2048
	s_add_i32 m0, s76, 49152
	s_nop 0
	global_load_lds_dwordx4 v[110:111], off
	v_lshl_add_u64 v[110:111], v[110:111], 0, s[78:79]
	s_add_i32 m0, s77, 49152
	s_nop 0
	global_load_lds_dwordx4 v[112:113], off
	v_lshl_add_u64 v[112:113], v[112:113], 0, s[78:79]
	s_add_i32 m0, s77, 50176
	s_nop 0
	global_load_lds_dwordx4 v[114:115], off
	v_lshl_add_u64 v[114:115], v[114:115], 0, s[78:79]
	s_waitcnt lgkmcnt(3)
	v_mfma_f32_16x16x32_bf16 v[120:123], v[128:131], v[136:139], v[120:123]
	v_mfma_f32_16x16x32_bf16 v[124:127], v[128:131], v[144:147], v[124:127]
	s_waitcnt lgkmcnt(0)
	v_mfma_f32_16x16x32_bf16 v[120:123], v[132:135], v[140:143], v[120:123]
	v_mfma_f32_16x16x32_bf16 v[124:127], v[132:135], v[148:151], v[124:127]
	s_waitcnt vmcnt(9)
	s_barrier
	ds_read_b128 v[152:155], v100
	ds_read_b128 v[160:163], v105 offset:0
	ds_read_b128 v[168:171], v105 offset:2048
	ds_read_b128 v[156:159], v192
	ds_read_b128 v[164:167], v197 offset:0
	ds_read_b128 v[172:175], v197 offset:2048
	s_add_i32 m0, s76, 73728
	s_nop 0
	global_load_lds_dwordx4 v[110:111], off
	v_lshl_add_u64 v[110:111], v[110:111], 0, s[78:79]
	s_add_i32 m0, s77, 73728
	s_nop 0
	global_load_lds_dwordx4 v[112:113], off
	v_lshl_add_u64 v[112:113], v[112:113], 0, s[78:79]
	s_add_i32 m0, s77, 74752
	s_nop 0
	global_load_lds_dwordx4 v[114:115], off
	v_lshl_add_u64 v[114:115], v[114:115], 0, s[78:79]
	s_waitcnt lgkmcnt(3)
	v_mfma_f32_16x16x32_bf16 v[120:123], v[152:155], v[160:163], v[120:123]
	v_mfma_f32_16x16x32_bf16 v[124:127], v[152:155], v[168:171], v[124:127]
	s_waitcnt lgkmcnt(0)
	v_mfma_f32_16x16x32_bf16 v[120:123], v[156:159], v[164:167], v[120:123]
	v_mfma_f32_16x16x32_bf16 v[124:127], v[156:159], v[172:175], v[124:127]
	s_waitcnt vmcnt(9)
	s_barrier
	ds_read_b128 v[128:131], v96
	ds_read_b128 v[136:139], v101 offset:0
	ds_read_b128 v[144:147], v101 offset:2048
	ds_read_b128 v[132:135], v188
	ds_read_b128 v[140:143], v193 offset:0
	ds_read_b128 v[148:151], v193 offset:2048
	s_add_i32 m0, s76, 98304
	s_nop 0
	global_load_lds_dwordx4 v[110:111], off
	v_lshl_add_u64 v[110:111], v[110:111], 0, s[78:79]
	s_add_i32 m0, s77, 98304
	s_nop 0
	global_load_lds_dwordx4 v[112:113], off
	v_lshl_add_u64 v[112:113], v[112:113], 0, s[78:79]
	s_add_i32 m0, s77, 99328
	s_nop 0
	global_load_lds_dwordx4 v[114:115], off
	v_lshl_add_u64 v[114:115], v[114:115], 0, s[78:79]
	s_waitcnt lgkmcnt(3)
	v_mfma_f32_16x16x32_bf16 v[120:123], v[128:131], v[136:139], v[120:123]
	v_mfma_f32_16x16x32_bf16 v[124:127], v[128:131], v[144:147], v[124:127]
	s_waitcnt lgkmcnt(0)
	v_mfma_f32_16x16x32_bf16 v[120:123], v[132:135], v[140:143], v[120:123]
	v_mfma_f32_16x16x32_bf16 v[124:127], v[132:135], v[148:151], v[124:127]
	s_waitcnt vmcnt(9)
	s_barrier
	ds_read_b128 v[152:155], v97
	ds_read_b128 v[160:163], v102 offset:0
	ds_read_b128 v[168:171], v102 offset:2048
	ds_read_b128 v[156:159], v189
	ds_read_b128 v[164:167], v194 offset:0
	ds_read_b128 v[172:175], v194 offset:2048
	s_add_i32 m0, s76, 0
	s_nop 0
	global_load_lds_dwordx4 v[110:111], off
	v_lshl_add_u64 v[110:111], v[110:111], 0, s[78:79]
	s_add_i32 m0, s77, 0
	s_nop 0
	global_load_lds_dwordx4 v[112:113], off
	v_lshl_add_u64 v[112:113], v[112:113], 0, s[78:79]
	s_add_i32 m0, s77, 1024
	s_nop 0
	global_load_lds_dwordx4 v[114:115], off
	v_lshl_add_u64 v[114:115], v[114:115], 0, s[78:79]
	s_waitcnt lgkmcnt(3)
	v_mfma_f32_16x16x32_bf16 v[120:123], v[152:155], v[160:163], v[120:123]
	v_mfma_f32_16x16x32_bf16 v[124:127], v[152:155], v[168:171], v[124:127]
	s_waitcnt lgkmcnt(0)
	v_mfma_f32_16x16x32_bf16 v[120:123], v[156:159], v[164:167], v[120:123]
	v_mfma_f32_16x16x32_bf16 v[124:127], v[156:159], v[172:175], v[124:127]
	s_waitcnt vmcnt(9)
	s_barrier
; template <class F>
; __device__ __forceinline__ void small_gemm_ks(LAS unsigned char* lds, const bf16_t* A, int lda, const bf16_t* Bt, int ldb, int K, int N, int a_grp_cols, int bx, int G, int tid, const F& f) {
;     ...
;         for (int k0 = 0; k0 < KH; k0 += 32) { const bf16x8 av = *(const bf16x8*)(ap + k0);
; #pragma unroll
;             for (int nt = 0; nt < 2; ++nt) { const bf16x8 bv = *(const bf16x8*)(bp + (size_t)nt * 16 * ldb + k0); acc[nt] = __builtin_amdgcn_mfma_f32_16x16x32_bf16(av, bv, acc[nt], 0, 0, 0); } }
	ds_read_b128 v[128:131], v98
	ds_read_b128 v[136:139], v103 offset:0
	ds_read_b128 v[144:147], v103 offset:2048
	ds_read_b128 v[132:135], v190
	ds_read_b128 v[140:143], v195 offset:0
	ds_read_b128 v[148:151], v195 offset:2048
	s_add_i32 m0, s76, 24576
	s_nop 0
	global_load_lds_dwordx4 v[110:111], off
	v_lshl_add_u64 v[110:111], v[110:111], 0, s[78:79]
	s_add_i32 m0, s77, 24576
	s_nop 0
	global_load_lds_dwordx4 v[112:113], off
	v_lshl_add_u64 v[112:113], v[112:113], 0, s[78:79]
	s_add_i32 m0, s77, 25600
	s_nop 0
	global_load_lds_dwordx4 v[114:115], off
	v_lshl_add_u64 v[114:115], v[114:115], 0, s[78:79]
	s_waitcnt lgkmcnt(3)
	v_mfma_f32_16x16x32_bf16 v[120:123], v[128:131], v[136:139], v[120:123]
	v_mfma_f32_16x16x32_bf16 v[124:127], v[128:131], v[144:147], v[124:127]
	s_waitcnt lgkmcnt(0)
	v_mfma_f32_16x16x32_bf16 v[120:123], v[132:135], v[140:143], v[120:123]
	v_mfma_f32_16x16x32_bf16 v[124:127], v[132:135], v[148:151], v[124:127]
	s_waitcnt vmcnt(9)
	s_barrier
	ds_read_b128 v[152:155], v99
	ds_read_b128 v[160:163], v104 offset:0
	ds_read_b128 v[168:171], v104 offset:2048
	ds_read_b128 v[156:159], v191
	ds_read_b128 v[164:167], v196 offset:0
	ds_read_b128 v[172:175], v196 offset:2048
	s_add_i32 m0, s76, 49152
	s_nop 0
	global_load_lds_dwordx4 v[110:111], off
	v_lshl_add_u64 v[110:111], v[110:111], 0, s[78:79]
	s_add_i32 m0, s77, 49152
	s_nop 0
	global_load_lds_dwordx4 v[112:113], off
	v_lshl_add_u64 v[112:113], v[112:113], 0, s[78:79]
	s_add_i32 m0, s77, 50176
	s_nop 0
	global_load_lds_dwordx4 v[114:115], off
	v_lshl_add_u64 v[114:115], v[114:115], 0, s[78:79]
	s_waitcnt lgkmcnt(3)
	v_mfma_f32_16x16x32_bf16 v[120:123], v[152:155], v[160:163], v[120:123]
	v_mfma_f32_16x16x32_bf16 v[124:127], v[152:155], v[168:171], v[124:127]
	s_waitcnt lgkmcnt(0)
	v_mfma_f32_16x16x32_bf16 v[120:123], v[156:159], v[164:167], v[120:123]
	v_mfma_f32_16x16x32_bf16 v[124:127], v[156:159], v[172:175], v[124:127]
	s_waitcnt vmcnt(9)
	s_barrier
	ds_read_b128 v[128:131], v100
	ds_read_b128 v[136:139], v105 offset:0
	ds_read_b128 v[144:147], v105 offset:2048
	ds_read_b128 v[132:135], v192
	ds_read_b128 v[140:143], v197 offset:0
	ds_read_b128 v[148:151], v197 offset:2048
	s_add_i32 m0, s76, 73728
	s_nop 0
	global_load_lds_dwordx4 v[110:111], off
	v_lshl_add_u64 v[110:111], v[110:111], 0, s[78:79]
	s_add_i32 m0, s77, 73728
	s_nop 0
	global_load_lds_dwordx4 v[112:113], off
	v_lshl_add_u64 v[112:113], v[112:113], 0, s[78:79]
	s_add_i32 m0, s77, 74752
	s_nop 0
	global_load_lds_dwordx4 v[114:115], off
	v_lshl_add_u64 v[114:115], v[114:115], 0, s[78:79]
	s_waitcnt lgkmcnt(3)
	v_mfma_f32_16x16x32_bf16 v[120:123], v[128:131], v[136:139], v[120:123]
	v_mfma_f32_16x16x32_bf16 v[124:127], v[128:131], v[144:147], v[124:127]
	s_waitcnt lgkmcnt(0)
	v_mfma_f32_16x16x32_bf16 v[120:123], v[132:135], v[140:143], v[120:123]
	v_mfma_f32_16x16x32_bf16 v[124:127], v[132:135], v[148:151], v[124:127]
	s_waitcnt vmcnt(9)
	s_barrier
	ds_read_b128 v[152:155], v96
	ds_read_b128 v[160:163], v101 offset:0
	ds_read_b128 v[168:171], v101 offset:2048
	ds_read_b128 v[156:159], v188
	ds_read_b128 v[164:167], v193 offset:0
	ds_read_b128 v[172:175], v193 offset:2048
	s_add_i32 m0, s76, 98304
	s_nop 0
	global_load_lds_dwordx4 v[110:111], off
	v_lshl_add_u64 v[110:111], v[110:111], 0, s[78:79]
	s_add_i32 m0, s77, 98304
	s_nop 0
	global_load_lds_dwordx4 v[112:113], off
	v_lshl_add_u64 v[112:113], v[112:113], 0, s[78:79]
	s_add_i32 m0, s77, 99328
	s_nop 0
	global_load_lds_dwordx4 v[114:115], off
	v_lshl_add_u64 v[114:115], v[114:115], 0, s[78:79]
	s_waitcnt lgkmcnt(3)
	v_mfma_f32_16x16x32_bf16 v[120:123], v[152:155], v[160:163], v[120:123]
	v_mfma_f32_16x16x32_bf16 v[124:127], v[152:155], v[168:171], v[124:127]
	s_waitcnt lgkmcnt(0)
	v_mfma_f32_16x16x32_bf16 v[120:123], v[156:159], v[164:167], v[120:123]
	v_mfma_f32_16x16x32_bf16 v[124:127], v[156:159], v[172:175], v[124:127]
	s_waitcnt vmcnt(9)
	s_barrier
; #define LAS __attribute__((address_space(3)))
; #define LDS_SYNC() do { asm volatile("s_waitcnt lgkmcnt(0)" ::: "memory"); __builtin_amdgcn_s_barrier(); asm volatile("" ::: "memory"); } while (0)
; template <class F>
; __device__ __forceinline__ void small_gemm_ks(LAS unsigned char* lds, const bf16_t* A, int lda, const bf16_t* Bt, int ldb, int K, int N, int a_grp_cols, int bx, int G, int tid, const F& f) {
;     ...
;         for (int k0 = 0; k0 < KH; k0 += 32) { const bf16x8 av = *(const bf16x8*)(ap + k0);
; #pragma unroll
;             for (int nt = 0; nt < 2; ++nt) { const bf16x8 bv = *(const bf16x8*)(bp + (size_t)nt * 16 * ldb + k0); acc[nt] = __builtin_amdgcn_mfma_f32_16x16x32_bf16(av, bv, acc[nt], 0, 0, 0); } }
;         if (kh == 1) { *(LAS f32x4*)(lds + ((wq * 2 + 0) * 64 + lane) * 16) = acc[0]; *(LAS f32x4*)(lds + ((wq * 2 + 1) * 64 + lane) * 16) = acc[1]; }
;         LDS_SYNC();
	ds_read_b128 v[128:131], v97
	ds_read_b128 v[136:139], v102 offset:0
	ds_read_b128 v[144:147], v102 offset:2048
	ds_read_b128 v[132:135], v189
	ds_read_b128 v[140:143], v194 offset:0
	ds_read_b128 v[148:151], v194 offset:2048
	s_add_i32 m0, s76, 0
	s_nop 0
	global_load_lds_dwordx4 v[110:111], off
	v_lshl_add_u64 v[110:111], v[110:111], 0, s[78:79]
	s_add_i32 m0, s77, 0
	s_nop 0
	global_load_lds_dwordx4 v[112:113], off
	v_lshl_add_u64 v[112:113], v[112:113], 0, s[78:79]
	s_add_i32 m0, s77, 1024
	s_nop 0
	global_load_lds_dwordx4 v[114:115], off
	v_lshl_add_u64 v[114:115], v[114:115], 0, s[78:79]
	s_waitcnt lgkmcnt(3)
	v_mfma_f32_16x16x32_bf16 v[120:123], v[128:131], v[136:139], v[120:123]
	v_mfma_f32_16x16x32_bf16 v[124:127], v[128:131], v[144:147], v[124:127]
	s_waitcnt lgkmcnt(0)
	v_mfma_f32_16x16x32_bf16 v[120:123], v[132:135], v[140:143], v[120:123]
	v_mfma_f32_16x16x32_bf16 v[124:127], v[132:135], v[148:151], v[124:127]
	s_waitcnt vmcnt(9)
	s_barrier
	ds_read_b128 v[152:155], v98
	ds_read_b128 v[160:163], v103 offset:0
	ds_read_b128 v[168:171], v103 offset:2048
	ds_read_b128 v[156:159], v190
	ds_read_b128 v[164:167], v195 offset:0
	ds_read_b128 v[172:175], v195 offset:2048
	s_add_i32 m0, s76, 24576
	s_nop 0
	global_load_lds_dwordx4 v[110:111], off
	v_lshl_add_u64 v[110:111], v[110:111], 0, s[78:79]
	s_add_i32 m0, s77, 24576
	s_nop 0
	global_load_lds_dwordx4 v[112:113], off
	v_lshl_add_u64 v[112:113], v[112:113], 0, s[78:79]
	s_add_i32 m0, s77, 25600
	s_nop 0
	global_load_lds_dwordx4 v[114:115], off
	v_lshl_add_u64 v[114:115], v[114:115], 0, s[78:79]
	s_waitcnt lgkmcnt(3)
	v_mfma_f32_16x16x32_bf16 v[120:123], v[152:155], v[160:163], v[120:123]
	v_mfma_f32_16x16x32_bf16 v[124:127], v[152:155], v[168:171], v[124:127]
	s_waitcnt lgkmcnt(0)
	v_mfma_f32_16x16x32_bf16 v[120:123], v[156:159], v[164:167], v[120:123]
	v_mfma_f32_16x16x32_bf16 v[124:127], v[156:159], v[172:175], v[124:127]
	s_waitcnt vmcnt(9)
	s_barrier
	ds_read_b128 v[128:131], v99
	ds_read_b128 v[136:139], v104 offset:0
	ds_read_b128 v[144:147], v104 offset:2048
	ds_read_b128 v[132:135], v191
	ds_read_b128 v[140:143], v196 offset:0
	ds_read_b128 v[148:151], v196 offset:2048
	s_waitcnt lgkmcnt(3)
	v_mfma_f32_16x16x32_bf16 v[120:123], v[128:131], v[136:139], v[120:123]
	v_mfma_f32_16x16x32_bf16 v[124:127], v[128:131], v[144:147], v[124:127]
	s_waitcnt lgkmcnt(0)
	v_mfma_f32_16x16x32_bf16 v[120:123], v[132:135], v[140:143], v[120:123]
	v_mfma_f32_16x16x32_bf16 v[124:127], v[132:135], v[148:151], v[124:127]
	s_waitcnt vmcnt(6)
	s_barrier
	ds_read_b128 v[152:155], v100
	ds_read_b128 v[160:163], v105 offset:0
	ds_read_b128 v[168:171], v105 offset:2048
	ds_read_b128 v[156:159], v192
	ds_read_b128 v[164:167], v197 offset:0
	ds_read_b128 v[172:175], v197 offset:2048
	s_waitcnt lgkmcnt(3)
	v_mfma_f32_16x16x32_bf16 v[120:123], v[152:155], v[160:163], v[120:123]
	v_mfma_f32_16x16x32_bf16 v[124:127], v[152:155], v[168:171], v[124:127]
	s_waitcnt lgkmcnt(0)
	v_mfma_f32_16x16x32_bf16 v[120:123], v[156:159], v[164:167], v[120:123]
	v_mfma_f32_16x16x32_bf16 v[124:127], v[156:159], v[172:175], v[124:127]
	s_waitcnt vmcnt(3)
	s_barrier
	ds_read_b128 v[128:131], v96
	ds_read_b128 v[136:139], v101 offset:0
	ds_read_b128 v[144:147], v101 offset:2048
	ds_read_b128 v[132:135], v188
	ds_read_b128 v[140:143], v193 offset:0
	ds_read_b128 v[148:151], v193 offset:2048
	s_waitcnt lgkmcnt(3)
	v_mfma_f32_16x16x32_bf16 v[120:123], v[128:131], v[136:139], v[120:123]
	v_mfma_f32_16x16x32_bf16 v[124:127], v[128:131], v[144:147], v[124:127]
	s_waitcnt lgkmcnt(0)
	v_mfma_f32_16x16x32_bf16 v[120:123], v[132:135], v[140:143], v[120:123]
	v_mfma_f32_16x16x32_bf16 v[124:127], v[132:135], v[148:151], v[124:127]
	s_waitcnt vmcnt(0)
	s_barrier
	ds_read_b128 v[152:155], v97
	ds_read_b128 v[160:163], v102 offset:0
	ds_read_b128 v[168:171], v102 offset:2048
	ds_read_b128 v[156:159], v189
	ds_read_b128 v[164:167], v194 offset:0
	ds_read_b128 v[172:175], v194 offset:2048
	s_waitcnt lgkmcnt(3)
	v_mfma_f32_16x16x32_bf16 v[120:123], v[152:155], v[160:163], v[120:123]
	v_mfma_f32_16x16x32_bf16 v[124:127], v[152:155], v[168:171], v[124:127]
	s_waitcnt lgkmcnt(0)
	v_mfma_f32_16x16x32_bf16 v[120:123], v[156:159], v[164:167], v[120:123]
	v_mfma_f32_16x16x32_bf16 v[124:127], v[156:159], v[172:175], v[124:127]
	s_barrier
	s_lshl_b32 s59, s82, 11
	s_lshl_b32 s62, s83, 1
	s_add_i32 s59, s59, s62
	s_add_u32 s60, s54, s59
	s_addc_u32 s61, s55, 0
	s_add_u32 s60, s60, 0x5700000
	s_addc_u32 s61, s61, 0
	v_lshl_add_u64 v[176:177], s[60:61], 0, v[106:107]
	s_mov_b32 s62, 0x1000
	s_mov_b32 s63, 0
	v_lshl_add_u64 v[178:179], v[176:177], 0, s[62:63]
	s_cmp_eq_u32 s70, 0
	s_cbranch_scc1 .Lsg_dn0_lo
	s_nop 4
	ds_write_b128 v109, v[120:123]
	ds_write_b128 v109, v[124:127] offset:1024
	s_waitcnt lgkmcnt(0)
	s_barrier
	s_branch .Lsg_dn0_done

; template <int WM, int WN, int NT, class F>
; __device__ __forceinline__ void small_gemm(const bf16_t* A, int lda, const bf16_t* Bt, int ldb, int K, int N, int a_grp_cols, int bx, int G, int tid, const F& f) {
;     static_assert(WM * WN == 8, "8 waves");
;     const int lane = tid & 63, w = __builtin_amdgcn_readfirstlane(tid >> 6), c = lane & 15, g = lane >> 4, wm = w / WN, wn = w % WN;
;     constexpr int TM = 16 * WM, TN = 16 * NT * WN;
;     const int ntn = N / TN, ntiles = (MS / TM) * ntn;
;     for (int t = bx; t < ntiles; t += G) {
;         const int row0 = MP + (t / ntn) * TM + wm * 16, n0 = (t % ntn) * TN + wn * 16 * NT;
;         const bf16_t* ap = A + (size_t)(row0 + c) * lda + (n0 >> 8) * a_grp_cols + 8 * g;
;         const bf16_t* bp = Bt + (size_t)(n0 + c) * ldb + 8 * g;
;         f32x4 acc[NT];
; #pragma unroll
;         for (int nt = 0; nt < NT; ++nt) acc[nt] = (f32x4){0.f, 0.f, 0.f, 0.f};
; #pragma unroll 8
;         for (int k0 = 0; k0 < K; k0 += 32) { const bf16x8 av = *(const bf16x8*)(ap + k0);
; #pragma unroll
;             for (int nt = 0; nt < NT; ++nt) { const bf16x8 bv = *(const bf16x8*)(bp + (size_t)nt * 16 * ldb + k0); acc[nt] = __builtin_amdgcn_mfma_f32_16x16x32_bf16(av, bv, acc[nt], 0, 0, 0); } }
.LBB0_1032:
	s_or_b64 exec, exec, s[6:7]
	v_readlane_b32 s0, v235, 5
	v_mov_b32_e32 v32, v208
	v_readlane_b32 s1, v235, 6
	s_waitcnt lgkmcnt(0)
	s_barrier
	s_load_dwordx2 s[6:7], s[0:1], 0xa0
	s_load_dwordx2 s[16:17], s[0:1], 0x60
	v_readfirstlane_b32 s0, v32
	v_and_b32_e32 v33, 15, v32
	s_waitcnt lgkmcnt(0)
	s_add_u32 s18, s6, 0x9900000
	s_addc_u32 s19, s7, 0
	s_add_u32 s20, s6, 0xba00000
	s_addc_u32 s21, s7, 0
	s_add_u32 s22, s6, 0x3600000
	s_addc_u32 s23, s7, 0
	s_and_b64 vcc, exec, s[88:89]
	s_cbranch_vccnz .LBB0_1229
	s_lshr_b32 s0, s0, 6
	v_and_b32_e32 v0, 63, v32
	v_lshrrev_b32_e32 v1, 3, v0
	v_and_b32_e32 v2, 7, v0
	v_and_b32_e32 v23, 6, v1
	v_xor_b32_e32 v2, v2, v23
	v_lshlrev_b32_e32 v4, 11, v1
	v_lshl_add_u32 v4, v2, 4, v4
	v_mov_b32_e32 v5, 0
	v_and_b32_e32 v1, 15, v0
	v_lshrrev_b32_e32 v2, 4, v0
	v_and_b32_e32 v23, 6, v1
	v_xor_b32_e32 v23, v2, v23
	v_lshrrev_b32_e32 v22, 3, v1
	v_lshlrev_b32_e32 v22, 10, v22
	v_lshl_add_u32 v22, v23, 4, v22
	v_and_b32_e32 v23, 7, v1
	v_lshl_add_u32 v22, v23, 7, v22
	s_lshr_b32 s1, s0, 1
	s_and_b32 s27, s0, 1
	s_lshl_b32 s24, s1, 11
	s_lshl_b32 s25, s27, 13
	s_add_i32 s25, s25, 0x2000
	v_add_u32_e32 v12, s24, v22
	v_add_u32_e32 v17, s25, v22
	v_add_u32_e32 v13, s24, v22
	v_add_u32_e32 v18, s25, v22
	v_add_u32_e32 v14, s24, v22
	v_add_u32_e32 v19, s25, v22
	v_add_u32_e32 v15, s24, v22
	v_add_u32_e32 v20, s25, v22
	v_add_u32_e32 v16, s24, v22
	v_add_u32_e32 v21, s25, v22
	v_add_u32_e32 v13, 24576, v13
	v_add_u32_e32 v18, 24576, v18
	v_add_u32_e32 v14, 49152, v14
	v_add_u32_e32 v19, 49152, v19
	v_add_u32_e32 v15, 73728, v15
	v_add_u32_e32 v20, 73728, v20
	v_add_u32_e32 v16, 98304, v16
	v_add_u32_e32 v21, 98304, v21
	v_xor_b32_e32 v144, 64, v12
	v_xor_b32_e32 v149, 64, v17
	v_xor_b32_e32 v145, 64, v13
	v_xor_b32_e32 v150, 64, v18
	v_xor_b32_e32 v146, 64, v14
	v_xor_b32_e32 v151, 64, v19
	v_xor_b32_e32 v147, 64, v15
	v_xor_b32_e32 v152, 64, v20
	v_xor_b32_e32 v148, 64, v16
	v_xor_b32_e32 v153, 64, v21
	s_lshl_b32 s33, s1, 4
	v_lshl_add_u32 v34, v2, 2, s33
	v_lshlrev_b32_e32 v34, 11, v34
	s_lshl_b32 s33, s27, 6
	v_add_u32_e32 v35, s33, v1
	v_lshl_add_u32 v34, v35, 1, v34
	v_lshlrev_b32_e32 v86, 2, v35
	v_mov_b32_e32 v35, 0
	s_lshl_b32 s24, s0, 10
	s_lshl_b32 s25, s0, 11
	s_add_i32 s25, s25, 0x2000
	s_mov_b32 s4, 0x80
	s_mov_b32 s5, 0
	s_movk_i32 s3, 0x7fff
	s_mov_b32 s35, s2
.Lsg_hin_tile:
	s_lshr_b32 s1, s35, 5
	s_and_b32 s27, s35, 31
	s_lshl_b32 s1, s1, 6
	s_add_i32 s1, s1, 0x4000
	s_lshr_b32 s36, s27, 3
	s_lshl_b32 s33, s0, 3
	s_add_i32 s33, s33, s1
	s_lshl_b32 s33, s33, 11
	s_add_u32 s10, s6, s33
	s_addc_u32 s11, s7, 0
	s_add_u32 s10, s10, 0x7800000
	s_addc_u32 s11, s11, 0
	v_lshl_add_u64 v[6:7], s[10:11], 0, v[4:5]
	s_lshl_b32 s33, s27, 7
	s_lshl_b32 s34, s0, 4
	s_add_i32 s33, s33, s34
	s_lshl_b32 s33, s33, 11
	s_add_u32 s10, s6, s33
	s_addc_u32 s11, s7, 0
	s_add_u32 s10, s10, 0x2280000
	s_addc_u32 s11, s11, 0
	v_lshl_add_u64 v[8:9], s[10:11], 0, v[4:5]
	s_add_u32 s10, s10, 0x4000
	s_addc_u32 s11, s11, 0
	v_lshl_add_u64 v[10:11], s[10:11], 0, v[4:5]
	s_and_b32 s33, s35, 7
	s_lshl_b32 s34, s33, 9
	v_add_u32_e32 v1, s34, v86
	v_add_u32_e32 v2, 0x1000, v1
	s_waitcnt vmcnt(0)
	global_load_dword v128, v1, s[16:17] offset:0
	global_load_dword v132, v2, s[16:17] offset:0
	global_load_dword v129, v1, s[16:17] offset:64
	global_load_dword v133, v2, s[16:17] offset:64
	global_load_dword v130, v1, s[16:17] offset:128
	global_load_dword v134, v2, s[16:17] offset:128
	global_load_dword v131, v1, s[16:17] offset:192
	global_load_dword v135, v2, s[16:17] offset:192
	v_mov_b32_e32 v24, 0
	v_mov_b32_e32 v25, 0
	v_mov_b32_e32 v26, 0
	v_mov_b32_e32 v27, 0
	v_mov_b32_e32 v28, 0
	v_mov_b32_e32 v29, 0
	v_mov_b32_e32 v30, 0
	v_mov_b32_e32 v31, 0
	v_mov_b32_e32 v36, 0
	v_mov_b32_e32 v37, 0
	v_mov_b32_e32 v38, 0
	v_mov_b32_e32 v39, 0
	v_mov_b32_e32 v40, 0
	v_mov_b32_e32 v41, 0
	v_mov_b32_e32 v42, 0
	v_mov_b32_e32 v43, 0
	s_add_i32 m0, s24, 0
	s_nop 0
	global_load_lds_dwordx4 v[6:7], off
	v_lshl_add_u64 v[6:7], v[6:7], 0, s[4:5]
	s_add_i32 m0, s25, 0
	s_nop 0
	global_load_lds_dwordx4 v[8:9], off
	v_lshl_add_u64 v[8:9], v[8:9], 0, s[4:5]
	s_add_i32 m0, s25, 1024
	s_nop 0
	global_load_lds_dwordx4 v[10:11], off
	v_lshl_add_u64 v[10:11], v[10:11], 0, s[4:5]
	s_add_i32 m0, s24, 24576
	s_nop 0
	global_load_lds_dwordx4 v[6:7], off
	v_lshl_add_u64 v[6:7], v[6:7], 0, s[4:5]
	s_add_i32 m0, s25, 24576
	s_nop 0
	global_load_lds_dwordx4 v[8:9], off
	v_lshl_add_u64 v[8:9], v[8:9], 0, s[4:5]
	s_add_i32 m0, s25, 25600
	s_nop 0
	global_load_lds_dwordx4 v[10:11], off
	v_lshl_add_u64 v[10:11], v[10:11], 0, s[4:5]
	s_add_i32 m0, s24, 49152
	s_nop 0
	global_load_lds_dwordx4 v[6:7], off
	v_lshl_add_u64 v[6:7], v[6:7], 0, s[4:5]
	s_add_i32 m0, s25, 49152
	s_nop 0
	global_load_lds_dwordx4 v[8:9], off
	v_lshl_add_u64 v[8:9], v[8:9], 0, s[4:5]
	s_add_i32 m0, s25, 50176
	s_nop 0
	global_load_lds_dwordx4 v[10:11], off
	v_lshl_add_u64 v[10:11], v[10:11], 0, s[4:5]
	s_add_i32 m0, s24, 73728
	s_nop 0
	global_load_lds_dwordx4 v[6:7], off
	v_lshl_add_u64 v[6:7], v[6:7], 0, s[4:5]
	s_add_i32 m0, s25, 73728
	s_nop 0
	global_load_lds_dwordx4 v[8:9], off
	v_lshl_add_u64 v[8:9], v[8:9], 0, s[4:5]
	s_add_i32 m0, s25, 74752
	s_nop 0
	global_load_lds_dwordx4 v[10:11], off
	v_lshl_add_u64 v[10:11], v[10:11], 0, s[4:5]
	s_waitcnt vmcnt(9)
	s_barrier
; template <int WM, int WN, int NT, class F>
; __device__ __forceinline__ void small_gemm(const bf16_t* A, int lda, const bf16_t* Bt, int ldb, int K, int N, int a_grp_cols, int bx, int G, int tid, const F& f) {
;     ...
; #pragma unroll 8
;         for (int k0 = 0; k0 < K; k0 += 32) { const bf16x8 av = *(const bf16x8*)(ap + k0);
; #pragma unroll
;             for (int nt = 0; nt < NT; ++nt) { const bf16x8 bv = *(const bf16x8*)(bp + (size_t)nt * 16 * ldb + k0); acc[nt] = __builtin_amdgcn_mfma_f32_16x16x32_bf16(av, bv, acc[nt], 0, 0, 0); } }
	ds_read_b128 v[44:47], v12
	ds_read_b128 v[52:55], v17 offset:0
	ds_read_b128 v[60:63], v17 offset:2048
	ds_read_b128 v[68:71], v17 offset:4096
	ds_read_b128 v[76:79], v17 offset:6144
	ds_read_b128 v[48:51], v144
	ds_read_b128 v[56:59], v149 offset:0
	ds_read_b128 v[64:67], v149 offset:2048
	ds_read_b128 v[72:75], v149 offset:4096
	ds_read_b128 v[80:83], v149 offset:6144
	s_add_i32 m0, s24, 98304
	s_nop 0
	global_load_lds_dwordx4 v[6:7], off
	v_lshl_add_u64 v[6:7], v[6:7], 0, s[4:5]
	s_add_i32 m0, s25, 98304
	s_nop 0
	global_load_lds_dwordx4 v[8:9], off
	v_lshl_add_u64 v[8:9], v[8:9], 0, s[4:5]
	s_add_i32 m0, s25, 99328
	s_nop 0
	global_load_lds_dwordx4 v[10:11], off
	v_lshl_add_u64 v[10:11], v[10:11], 0, s[4:5]
	s_waitcnt lgkmcnt(5)
	v_mfma_f32_16x16x32_bf16 v[24:27], v[44:47], v[52:55], v[24:27]
	v_mfma_f32_16x16x32_bf16 v[28:31], v[44:47], v[60:63], v[28:31]
	v_mfma_f32_16x16x32_bf16 v[36:39], v[44:47], v[68:71], v[36:39]
	v_mfma_f32_16x16x32_bf16 v[40:43], v[44:47], v[76:79], v[40:43]
	s_waitcnt lgkmcnt(0)
	v_mfma_f32_16x16x32_bf16 v[24:27], v[48:51], v[56:59], v[24:27]
	v_mfma_f32_16x16x32_bf16 v[28:31], v[48:51], v[64:67], v[28:31]
	v_mfma_f32_16x16x32_bf16 v[36:39], v[48:51], v[72:75], v[36:39]
	v_mfma_f32_16x16x32_bf16 v[40:43], v[48:51], v[80:83], v[40:43]
	s_waitcnt vmcnt(9)
	s_barrier
	ds_read_b128 v[88:91], v13
	ds_read_b128 v[96:99], v18 offset:0
	ds_read_b128 v[104:107], v18 offset:2048
	ds_read_b128 v[112:115], v18 offset:4096
	ds_read_b128 v[120:123], v18 offset:6144
	ds_read_b128 v[92:95], v145
	ds_read_b128 v[100:103], v150 offset:0
	ds_read_b128 v[108:111], v150 offset:2048
	ds_read_b128 v[116:119], v150 offset:4096
	ds_read_b128 v[124:127], v150 offset:6144
	s_add_i32 m0, s24, 0
	s_nop 0
	global_load_lds_dwordx4 v[6:7], off
	v_lshl_add_u64 v[6:7], v[6:7], 0, s[4:5]
	s_add_i32 m0, s25, 0
	s_nop 0
	global_load_lds_dwordx4 v[8:9], off
	v_lshl_add_u64 v[8:9], v[8:9], 0, s[4:5]
	s_add_i32 m0, s25, 1024
	s_nop 0
	global_load_lds_dwordx4 v[10:11], off
	v_lshl_add_u64 v[10:11], v[10:11], 0, s[4:5]
	s_waitcnt lgkmcnt(5)
	v_mfma_f32_16x16x32_bf16 v[24:27], v[88:91], v[96:99], v[24:27]
	v_mfma_f32_16x16x32_bf16 v[28:31], v[88:91], v[104:107], v[28:31]
	v_mfma_f32_16x16x32_bf16 v[36:39], v[88:91], v[112:115], v[36:39]
	v_mfma_f32_16x16x32_bf16 v[40:43], v[88:91], v[120:123], v[40:43]
	s_waitcnt lgkmcnt(0)
	v_mfma_f32_16x16x32_bf16 v[24:27], v[92:95], v[100:103], v[24:27]
	v_mfma_f32_16x16x32_bf16 v[28:31], v[92:95], v[108:111], v[28:31]
	v_mfma_f32_16x16x32_bf16 v[36:39], v[92:95], v[116:119], v[36:39]
	v_mfma_f32_16x16x32_bf16 v[40:43], v[92:95], v[124:127], v[40:43]
	s_waitcnt vmcnt(9)
	s_barrier
	ds_read_b128 v[44:47], v14
	ds_read_b128 v[52:55], v19 offset:0
	ds_read_b128 v[60:63], v19 offset:2048
	ds_read_b128 v[68:71], v19 offset:4096
	ds_read_b128 v[76:79], v19 offset:6144
	ds_read_b128 v[48:51], v146
	ds_read_b128 v[56:59], v151 offset:0
	ds_read_b128 v[64:67], v151 offset:2048
	ds_read_b128 v[72:75], v151 offset:4096
	ds_read_b128 v[80:83], v151 offset:6144
	s_add_i32 m0, s24, 24576
	s_nop 0
	global_load_lds_dwordx4 v[6:7], off
	v_lshl_add_u64 v[6:7], v[6:7], 0, s[4:5]
	s_add_i32 m0, s25, 24576
	s_nop 0
	global_load_lds_dwordx4 v[8:9], off
	v_lshl_add_u64 v[8:9], v[8:9], 0, s[4:5]
	s_add_i32 m0, s25, 25600
	s_nop 0
	global_load_lds_dwordx4 v[10:11], off
	v_lshl_add_u64 v[10:11], v[10:11], 0, s[4:5]
	s_waitcnt lgkmcnt(5)
	v_mfma_f32_16x16x32_bf16 v[24:27], v[44:47], v[52:55], v[24:27]
	v_mfma_f32_16x16x32_bf16 v[28:31], v[44:47], v[60:63], v[28:31]
	v_mfma_f32_16x16x32_bf16 v[36:39], v[44:47], v[68:71], v[36:39]
	v_mfma_f32_16x16x32_bf16 v[40:43], v[44:47], v[76:79], v[40:43]
	s_waitcnt lgkmcnt(0)
	v_mfma_f32_16x16x32_bf16 v[24:27], v[48:51], v[56:59], v[24:27]
	v_mfma_f32_16x16x32_bf16 v[28:31], v[48:51], v[64:67], v[28:31]
	v_mfma_f32_16x16x32_bf16 v[36:39], v[48:51], v[72:75], v[36:39]
	v_mfma_f32_16x16x32_bf16 v[40:43], v[48:51], v[80:83], v[40:43]
	s_waitcnt vmcnt(9)
	s_barrier
	ds_read_b128 v[88:91], v15
	ds_read_b128 v[96:99], v20 offset:0
	ds_read_b128 v[104:107], v20 offset:2048
	ds_read_b128 v[112:115], v20 offset:4096
	ds_read_b128 v[120:123], v20 offset:6144
	ds_read_b128 v[92:95], v147
	ds_read_b128 v[100:103], v152 offset:0
	ds_read_b128 v[108:111], v152 offset:2048
	ds_read_b128 v[116:119], v152 offset:4096
	ds_read_b128 v[124:127], v152 offset:6144
	s_add_i32 m0, s24, 49152
	s_nop 0
	global_load_lds_dwordx4 v[6:7], off
	v_lshl_add_u64 v[6:7], v[6:7], 0, s[4:5]
	s_add_i32 m0, s25, 49152
	s_nop 0
	global_load_lds_dwordx4 v[8:9], off
	v_lshl_add_u64 v[8:9], v[8:9], 0, s[4:5]
	s_add_i32 m0, s25, 50176
	s_nop 0
	global_load_lds_dwordx4 v[10:11], off
	v_lshl_add_u64 v[10:11], v[10:11], 0, s[4:5]
	s_waitcnt lgkmcnt(5)
	v_mfma_f32_16x16x32_bf16 v[24:27], v[88:91], v[96:99], v[24:27]
	v_mfma_f32_16x16x32_bf16 v[28:31], v[88:91], v[104:107], v[28:31]
	v_mfma_f32_16x16x32_bf16 v[36:39], v[88:91], v[112:115], v[36:39]
	v_mfma_f32_16x16x32_bf16 v[40:43], v[88:91], v[120:123], v[40:43]
	s_waitcnt lgkmcnt(0)
	v_mfma_f32_16x16x32_bf16 v[24:27], v[92:95], v[100:103], v[24:27]
	v_mfma_f32_16x16x32_bf16 v[28:31], v[92:95], v[108:111], v[28:31]
	v_mfma_f32_16x16x32_bf16 v[36:39], v[92:95], v[116:119], v[36:39]
	v_mfma_f32_16x16x32_bf16 v[40:43], v[92:95], v[124:127], v[40:43]
	s_waitcnt vmcnt(9)
	s_barrier
; template <int WM, int WN, int NT, class F>
; __device__ __forceinline__ void small_gemm(const bf16_t* A, int lda, const bf16_t* Bt, int ldb, int K, int N, int a_grp_cols, int bx, int G, int tid, const F& f) {
;     ...
; #pragma unroll 8
;         for (int k0 = 0; k0 < K; k0 += 32) { const bf16x8 av = *(const bf16x8*)(ap + k0);
; #pragma unroll
;             for (int nt = 0; nt < NT; ++nt) { const bf16x8 bv = *(const bf16x8*)(bp + (size_t)nt * 16 * ldb + k0); acc[nt] = __builtin_amdgcn_mfma_f32_16x16x32_bf16(av, bv, acc[nt], 0, 0, 0); } }
	ds_read_b128 v[44:47], v16
	ds_read_b128 v[52:55], v21 offset:0
	ds_read_b128 v[60:63], v21 offset:2048
	ds_read_b128 v[68:71], v21 offset:4096
	ds_read_b128 v[76:79], v21 offset:6144
	ds_read_b128 v[48:51], v148
	ds_read_b128 v[56:59], v153 offset:0
	ds_read_b128 v[64:67], v153 offset:2048
	ds_read_b128 v[72:75], v153 offset:4096
	ds_read_b128 v[80:83], v153 offset:6144
	s_add_i32 m0, s24, 73728
	s_nop 0
	global_load_lds_dwordx4 v[6:7], off
	v_lshl_add_u64 v[6:7], v[6:7], 0, s[4:5]
	s_add_i32 m0, s25, 73728
	s_nop 0
	global_load_lds_dwordx4 v[8:9], off
	v_lshl_add_u64 v[8:9], v[8:9], 0, s[4:5]
	s_add_i32 m0, s25, 74752
	s_nop 0
	global_load_lds_dwordx4 v[10:11], off
	v_lshl_add_u64 v[10:11], v[10:11], 0, s[4:5]
	s_waitcnt lgkmcnt(5)
	v_mfma_f32_16x16x32_bf16 v[24:27], v[44:47], v[52:55], v[24:27]
	v_mfma_f32_16x16x32_bf16 v[28:31], v[44:47], v[60:63], v[28:31]
	v_mfma_f32_16x16x32_bf16 v[36:39], v[44:47], v[68:71], v[36:39]
	v_mfma_f32_16x16x32_bf16 v[40:43], v[44:47], v[76:79], v[40:43]
	s_waitcnt lgkmcnt(0)
	v_mfma_f32_16x16x32_bf16 v[24:27], v[48:51], v[56:59], v[24:27]
	v_mfma_f32_16x16x32_bf16 v[28:31], v[48:51], v[64:67], v[28:31]
	v_mfma_f32_16x16x32_bf16 v[36:39], v[48:51], v[72:75], v[36:39]
	v_mfma_f32_16x16x32_bf16 v[40:43], v[48:51], v[80:83], v[40:43]
	s_waitcnt vmcnt(9)
	s_barrier
	ds_read_b128 v[88:91], v12
	ds_read_b128 v[96:99], v17 offset:0
	ds_read_b128 v[104:107], v17 offset:2048
	ds_read_b128 v[112:115], v17 offset:4096
	ds_read_b128 v[120:123], v17 offset:6144
	ds_read_b128 v[92:95], v144
	ds_read_b128 v[100:103], v149 offset:0
	ds_read_b128 v[108:111], v149 offset:2048
	ds_read_b128 v[116:119], v149 offset:4096
	ds_read_b128 v[124:127], v149 offset:6144
	s_add_i32 m0, s24, 98304
	s_nop 0
	global_load_lds_dwordx4 v[6:7], off
	v_lshl_add_u64 v[6:7], v[6:7], 0, s[4:5]
	s_add_i32 m0, s25, 98304
	s_nop 0
	global_load_lds_dwordx4 v[8:9], off
	v_lshl_add_u64 v[8:9], v[8:9], 0, s[4:5]
	s_add_i32 m0, s25, 99328
	s_nop 0
	global_load_lds_dwordx4 v[10:11], off
	v_lshl_add_u64 v[10:11], v[10:11], 0, s[4:5]
	s_waitcnt lgkmcnt(5)
	v_mfma_f32_16x16x32_bf16 v[24:27], v[88:91], v[96:99], v[24:27]
	v_mfma_f32_16x16x32_bf16 v[28:31], v[88:91], v[104:107], v[28:31]
	v_mfma_f32_16x16x32_bf16 v[36:39], v[88:91], v[112:115], v[36:39]
	v_mfma_f32_16x16x32_bf16 v[40:43], v[88:91], v[120:123], v[40:43]
	s_waitcnt lgkmcnt(0)
	v_mfma_f32_16x16x32_bf16 v[24:27], v[92:95], v[100:103], v[24:27]
	v_mfma_f32_16x16x32_bf16 v[28:31], v[92:95], v[108:111], v[28:31]
	v_mfma_f32_16x16x32_bf16 v[36:39], v[92:95], v[116:119], v[36:39]
	v_mfma_f32_16x16x32_bf16 v[40:43], v[92:95], v[124:127], v[40:43]
	s_waitcnt vmcnt(9)
	s_barrier
	ds_read_b128 v[44:47], v13
	ds_read_b128 v[52:55], v18 offset:0
	ds_read_b128 v[60:63], v18 offset:2048
	ds_read_b128 v[68:71], v18 offset:4096
	ds_read_b128 v[76:79], v18 offset:6144
	ds_read_b128 v[48:51], v145
	ds_read_b128 v[56:59], v150 offset:0
	ds_read_b128 v[64:67], v150 offset:2048
	ds_read_b128 v[72:75], v150 offset:4096
	ds_read_b128 v[80:83], v150 offset:6144
	s_add_i32 m0, s24, 0
	s_nop 0
	global_load_lds_dwordx4 v[6:7], off
	v_lshl_add_u64 v[6:7], v[6:7], 0, s[4:5]
	s_add_i32 m0, s25, 0
	s_nop 0
	global_load_lds_dwordx4 v[8:9], off
	v_lshl_add_u64 v[8:9], v[8:9], 0, s[4:5]
	s_add_i32 m0, s25, 1024
	s_nop 0
	global_load_lds_dwordx4 v[10:11], off
	v_lshl_add_u64 v[10:11], v[10:11], 0, s[4:5]
	s_waitcnt lgkmcnt(5)
	v_mfma_f32_16x16x32_bf16 v[24:27], v[44:47], v[52:55], v[24:27]
	v_mfma_f32_16x16x32_bf16 v[28:31], v[44:47], v[60:63], v[28:31]
	v_mfma_f32_16x16x32_bf16 v[36:39], v[44:47], v[68:71], v[36:39]
	v_mfma_f32_16x16x32_bf16 v[40:43], v[44:47], v[76:79], v[40:43]
	s_waitcnt lgkmcnt(0)
	v_mfma_f32_16x16x32_bf16 v[24:27], v[48:51], v[56:59], v[24:27]
	v_mfma_f32_16x16x32_bf16 v[28:31], v[48:51], v[64:67], v[28:31]
	v_mfma_f32_16x16x32_bf16 v[36:39], v[48:51], v[72:75], v[36:39]
	v_mfma_f32_16x16x32_bf16 v[40:43], v[48:51], v[80:83], v[40:43]
	s_waitcnt vmcnt(9)
	s_barrier
	ds_read_b128 v[88:91], v14
	ds_read_b128 v[96:99], v19 offset:0
	ds_read_b128 v[104:107], v19 offset:2048
	ds_read_b128 v[112:115], v19 offset:4096
	ds_read_b128 v[120:123], v19 offset:6144
	ds_read_b128 v[92:95], v146
	ds_read_b128 v[100:103], v151 offset:0
	ds_read_b128 v[108:111], v151 offset:2048
	ds_read_b128 v[116:119], v151 offset:4096
	ds_read_b128 v[124:127], v151 offset:6144
	s_add_i32 m0, s24, 24576
	s_nop 0
	global_load_lds_dwordx4 v[6:7], off
	v_lshl_add_u64 v[6:7], v[6:7], 0, s[4:5]
	s_add_i32 m0, s25, 24576
	s_nop 0
	global_load_lds_dwordx4 v[8:9], off
	v_lshl_add_u64 v[8:9], v[8:9], 0, s[4:5]
	s_add_i32 m0, s25, 25600
	s_nop 0
	global_load_lds_dwordx4 v[10:11], off
	v_lshl_add_u64 v[10:11], v[10:11], 0, s[4:5]
	s_waitcnt lgkmcnt(5)
	v_mfma_f32_16x16x32_bf16 v[24:27], v[88:91], v[96:99], v[24:27]
	v_mfma_f32_16x16x32_bf16 v[28:31], v[88:91], v[104:107], v[28:31]
	v_mfma_f32_16x16x32_bf16 v[36:39], v[88:91], v[112:115], v[36:39]
	v_mfma_f32_16x16x32_bf16 v[40:43], v[88:91], v[120:123], v[40:43]
	s_waitcnt lgkmcnt(0)
	v_mfma_f32_16x16x32_bf16 v[24:27], v[92:95], v[100:103], v[24:27]
	v_mfma_f32_16x16x32_bf16 v[28:31], v[92:95], v[108:111], v[28:31]
	v_mfma_f32_16x16x32_bf16 v[36:39], v[92:95], v[116:119], v[36:39]
	v_mfma_f32_16x16x32_bf16 v[40:43], v[92:95], v[124:127], v[40:43]
	s_waitcnt vmcnt(9)
	s_barrier
; template <int WM, int WN, int NT, class F>
; __device__ __forceinline__ void small_gemm(const bf16_t* A, int lda, const bf16_t* Bt, int ldb, int K, int N, int a_grp_cols, int bx, int G, int tid, const F& f) {
;     ...
; #pragma unroll 8
;         for (int k0 = 0; k0 < K; k0 += 32) { const bf16x8 av = *(const bf16x8*)(ap + k0);
; #pragma unroll
;             for (int nt = 0; nt < NT; ++nt) { const bf16x8 bv = *(const bf16x8*)(bp + (size_t)nt * 16 * ldb + k0); acc[nt] = __builtin_amdgcn_mfma_f32_16x16x32_bf16(av, bv, acc[nt], 0, 0, 0); } }
	ds_read_b128 v[44:47], v15
	ds_read_b128 v[52:55], v20 offset:0
	ds_read_b128 v[60:63], v20 offset:2048
	ds_read_b128 v[68:71], v20 offset:4096
	ds_read_b128 v[76:79], v20 offset:6144
	ds_read_b128 v[48:51], v147
	ds_read_b128 v[56:59], v152 offset:0
	ds_read_b128 v[64:67], v152 offset:2048
	ds_read_b128 v[72:75], v152 offset:4096
	ds_read_b128 v[80:83], v152 offset:6144
	s_add_i32 m0, s24, 49152
	s_nop 0
	global_load_lds_dwordx4 v[6:7], off
	v_lshl_add_u64 v[6:7], v[6:7], 0, s[4:5]
	s_add_i32 m0, s25, 49152
	s_nop 0
	global_load_lds_dwordx4 v[8:9], off
	v_lshl_add_u64 v[8:9], v[8:9], 0, s[4:5]
	s_add_i32 m0, s25, 50176
	s_nop 0
	global_load_lds_dwordx4 v[10:11], off
	v_lshl_add_u64 v[10:11], v[10:11], 0, s[4:5]
	s_waitcnt lgkmcnt(5)
	v_mfma_f32_16x16x32_bf16 v[24:27], v[44:47], v[52:55], v[24:27]
	v_mfma_f32_16x16x32_bf16 v[28:31], v[44:47], v[60:63], v[28:31]
	v_mfma_f32_16x16x32_bf16 v[36:39], v[44:47], v[68:71], v[36:39]
	v_mfma_f32_16x16x32_bf16 v[40:43], v[44:47], v[76:79], v[40:43]
	s_waitcnt lgkmcnt(0)
	v_mfma_f32_16x16x32_bf16 v[24:27], v[48:51], v[56:59], v[24:27]
	v_mfma_f32_16x16x32_bf16 v[28:31], v[48:51], v[64:67], v[28:31]
	v_mfma_f32_16x16x32_bf16 v[36:39], v[48:51], v[72:75], v[36:39]
	v_mfma_f32_16x16x32_bf16 v[40:43], v[48:51], v[80:83], v[40:43]
	s_waitcnt vmcnt(9)
	s_barrier
	ds_read_b128 v[88:91], v16
	ds_read_b128 v[96:99], v21 offset:0
	ds_read_b128 v[104:107], v21 offset:2048
	ds_read_b128 v[112:115], v21 offset:4096
	ds_read_b128 v[120:123], v21 offset:6144
	ds_read_b128 v[92:95], v148
	ds_read_b128 v[100:103], v153 offset:0
	ds_read_b128 v[108:111], v153 offset:2048
	ds_read_b128 v[116:119], v153 offset:4096
	ds_read_b128 v[124:127], v153 offset:6144
	s_add_i32 m0, s24, 73728
	s_nop 0
	global_load_lds_dwordx4 v[6:7], off
	v_lshl_add_u64 v[6:7], v[6:7], 0, s[4:5]
	s_add_i32 m0, s25, 73728
	s_nop 0
	global_load_lds_dwordx4 v[8:9], off
	v_lshl_add_u64 v[8:9], v[8:9], 0, s[4:5]
	s_add_i32 m0, s25, 74752
	s_nop 0
	global_load_lds_dwordx4 v[10:11], off
	v_lshl_add_u64 v[10:11], v[10:11], 0, s[4:5]
	s_waitcnt lgkmcnt(5)
	v_mfma_f32_16x16x32_bf16 v[24:27], v[88:91], v[96:99], v[24:27]
	v_mfma_f32_16x16x32_bf16 v[28:31], v[88:91], v[104:107], v[28:31]
	v_mfma_f32_16x16x32_bf16 v[36:39], v[88:91], v[112:115], v[36:39]
	v_mfma_f32_16x16x32_bf16 v[40:43], v[88:91], v[120:123], v[40:43]
	s_waitcnt lgkmcnt(0)
	v_mfma_f32_16x16x32_bf16 v[24:27], v[92:95], v[100:103], v[24:27]
	v_mfma_f32_16x16x32_bf16 v[28:31], v[92:95], v[108:111], v[28:31]
	v_mfma_f32_16x16x32_bf16 v[36:39], v[92:95], v[116:119], v[36:39]
	v_mfma_f32_16x16x32_bf16 v[40:43], v[92:95], v[124:127], v[40:43]
	s_waitcnt vmcnt(9)
	s_barrier
	ds_read_b128 v[44:47], v12
	ds_read_b128 v[52:55], v17 offset:0
	ds_read_b128 v[60:63], v17 offset:2048
	ds_read_b128 v[68:71], v17 offset:4096
	ds_read_b128 v[76:79], v17 offset:6144
	ds_read_b128 v[48:51], v144
	ds_read_b128 v[56:59], v149 offset:0
	ds_read_b128 v[64:67], v149 offset:2048
	ds_read_b128 v[72:75], v149 offset:4096
	ds_read_b128 v[80:83], v149 offset:6144
	s_add_i32 m0, s24, 98304
	s_nop 0
	global_load_lds_dwordx4 v[6:7], off
	v_lshl_add_u64 v[6:7], v[6:7], 0, s[4:5]
	s_add_i32 m0, s25, 98304
	s_nop 0
	global_load_lds_dwordx4 v[8:9], off
	v_lshl_add_u64 v[8:9], v[8:9], 0, s[4:5]
	s_add_i32 m0, s25, 99328
	s_nop 0
	global_load_lds_dwordx4 v[10:11], off
	v_lshl_add_u64 v[10:11], v[10:11], 0, s[4:5]
	s_waitcnt lgkmcnt(5)
	v_mfma_f32_16x16x32_bf16 v[24:27], v[44:47], v[52:55], v[24:27]
	v_mfma_f32_16x16x32_bf16 v[28:31], v[44:47], v[60:63], v[28:31]
	v_mfma_f32_16x16x32_bf16 v[36:39], v[44:47], v[68:71], v[36:39]
	v_mfma_f32_16x16x32_bf16 v[40:43], v[44:47], v[76:79], v[40:43]
	s_waitcnt lgkmcnt(0)
	v_mfma_f32_16x16x32_bf16 v[24:27], v[48:51], v[56:59], v[24:27]
	v_mfma_f32_16x16x32_bf16 v[28:31], v[48:51], v[64:67], v[28:31]
	v_mfma_f32_16x16x32_bf16 v[36:39], v[48:51], v[72:75], v[36:39]
	v_mfma_f32_16x16x32_bf16 v[40:43], v[48:51], v[80:83], v[40:43]
	s_waitcnt vmcnt(9)
	s_barrier
	ds_read_b128 v[88:91], v13
	ds_read_b128 v[96:99], v18 offset:0
	ds_read_b128 v[104:107], v18 offset:2048
	ds_read_b128 v[112:115], v18 offset:4096
	ds_read_b128 v[120:123], v18 offset:6144
	ds_read_b128 v[92:95], v145
	ds_read_b128 v[100:103], v150 offset:0
	ds_read_b128 v[108:111], v150 offset:2048
	ds_read_b128 v[116:119], v150 offset:4096
	ds_read_b128 v[124:127], v150 offset:6144
	s_add_i32 m0, s24, 0
	s_nop 0
	global_load_lds_dwordx4 v[6:7], off
	v_lshl_add_u64 v[6:7], v[6:7], 0, s[4:5]
	s_add_i32 m0, s25, 0
	s_nop 0
	global_load_lds_dwordx4 v[8:9], off
	v_lshl_add_u64 v[8:9], v[8:9], 0, s[4:5]
	s_add_i32 m0, s25, 1024
	s_nop 0
	global_load_lds_dwordx4 v[10:11], off
	v_lshl_add_u64 v[10:11], v[10:11], 0, s[4:5]
	s_waitcnt lgkmcnt(5)
	v_mfma_f32_16x16x32_bf16 v[24:27], v[88:91], v[96:99], v[24:27]
	v_mfma_f32_16x16x32_bf16 v[28:31], v[88:91], v[104:107], v[28:31]
	v_mfma_f32_16x16x32_bf16 v[36:39], v[88:91], v[112:115], v[36:39]
	v_mfma_f32_16x16x32_bf16 v[40:43], v[88:91], v[120:123], v[40:43]
	s_waitcnt lgkmcnt(0)
	v_mfma_f32_16x16x32_bf16 v[24:27], v[92:95], v[100:103], v[24:27]
	v_mfma_f32_16x16x32_bf16 v[28:31], v[92:95], v[108:111], v[28:31]
	v_mfma_f32_16x16x32_bf16 v[36:39], v[92:95], v[116:119], v[36:39]
	v_mfma_f32_16x16x32_bf16 v[40:43], v[92:95], v[124:127], v[40:43]
	s_waitcnt vmcnt(9)
	s_barrier
; template <int WM, int WN, int NT, class F>
; __device__ __forceinline__ void small_gemm(const bf16_t* A, int lda, const bf16_t* Bt, int ldb, int K, int N, int a_grp_cols, int bx, int G, int tid, const F& f) {
;     ...
; #pragma unroll 8
;         for (int k0 = 0; k0 < K; k0 += 32) { const bf16x8 av = *(const bf16x8*)(ap + k0);
; #pragma unroll
;             for (int nt = 0; nt < NT; ++nt) { const bf16x8 bv = *(const bf16x8*)(bp + (size_t)nt * 16 * ldb + k0); acc[nt] = __builtin_amdgcn_mfma_f32_16x16x32_bf16(av, bv, acc[nt], 0, 0, 0); } }
	ds_read_b128 v[44:47], v14
	ds_read_b128 v[52:55], v19 offset:0
	ds_read_b128 v[60:63], v19 offset:2048
	ds_read_b128 v[68:71], v19 offset:4096
	ds_read_b128 v[76:79], v19 offset:6144
	ds_read_b128 v[48:51], v146
	ds_read_b128 v[56:59], v151 offset:0
	ds_read_b128 v[64:67], v151 offset:2048
	ds_read_b128 v[72:75], v151 offset:4096
	ds_read_b128 v[80:83], v151 offset:6144
	s_waitcnt lgkmcnt(5)
	v_mfma_f32_16x16x32_bf16 v[24:27], v[44:47], v[52:55], v[24:27]
	v_mfma_f32_16x16x32_bf16 v[28:31], v[44:47], v[60:63], v[28:31]
	v_mfma_f32_16x16x32_bf16 v[36:39], v[44:47], v[68:71], v[36:39]
	v_mfma_f32_16x16x32_bf16 v[40:43], v[44:47], v[76:79], v[40:43]
	s_waitcnt lgkmcnt(0)
	v_mfma_f32_16x16x32_bf16 v[24:27], v[48:51], v[56:59], v[24:27]
	v_mfma_f32_16x16x32_bf16 v[28:31], v[48:51], v[64:67], v[28:31]
	v_mfma_f32_16x16x32_bf16 v[36:39], v[48:51], v[72:75], v[36:39]
	v_mfma_f32_16x16x32_bf16 v[40:43], v[48:51], v[80:83], v[40:43]
	s_waitcnt vmcnt(6)
	s_barrier
	ds_read_b128 v[88:91], v15
	ds_read_b128 v[96:99], v20 offset:0
	ds_read_b128 v[104:107], v20 offset:2048
	ds_read_b128 v[112:115], v20 offset:4096
	ds_read_b128 v[120:123], v20 offset:6144
	ds_read_b128 v[92:95], v147
	ds_read_b128 v[100:103], v152 offset:0
	ds_read_b128 v[108:111], v152 offset:2048
	ds_read_b128 v[116:119], v152 offset:4096
	ds_read_b128 v[124:127], v152 offset:6144
	s_waitcnt lgkmcnt(5)
	v_mfma_f32_16x16x32_bf16 v[24:27], v[88:91], v[96:99], v[24:27]
	v_mfma_f32_16x16x32_bf16 v[28:31], v[88:91], v[104:107], v[28:31]
	v_mfma_f32_16x16x32_bf16 v[36:39], v[88:91], v[112:115], v[36:39]
	v_mfma_f32_16x16x32_bf16 v[40:43], v[88:91], v[120:123], v[40:43]
	s_waitcnt lgkmcnt(0)
	v_mfma_f32_16x16x32_bf16 v[24:27], v[92:95], v[100:103], v[24:27]
	v_mfma_f32_16x16x32_bf16 v[28:31], v[92:95], v[108:111], v[28:31]
	v_mfma_f32_16x16x32_bf16 v[36:39], v[92:95], v[116:119], v[36:39]
	v_mfma_f32_16x16x32_bf16 v[40:43], v[92:95], v[124:127], v[40:43]
	s_waitcnt vmcnt(3)
	s_barrier
	ds_read_b128 v[44:47], v16
	ds_read_b128 v[52:55], v21 offset:0
	ds_read_b128 v[60:63], v21 offset:2048
	ds_read_b128 v[68:71], v21 offset:4096
	ds_read_b128 v[76:79], v21 offset:6144
	ds_read_b128 v[48:51], v148
	ds_read_b128 v[56:59], v153 offset:0
	ds_read_b128 v[64:67], v153 offset:2048
	ds_read_b128 v[72:75], v153 offset:4096
	ds_read_b128 v[80:83], v153 offset:6144
	s_waitcnt lgkmcnt(5)
	v_mfma_f32_16x16x32_bf16 v[24:27], v[44:47], v[52:55], v[24:27]
	v_mfma_f32_16x16x32_bf16 v[28:31], v[44:47], v[60:63], v[28:31]
	v_mfma_f32_16x16x32_bf16 v[36:39], v[44:47], v[68:71], v[36:39]
	v_mfma_f32_16x16x32_bf16 v[40:43], v[44:47], v[76:79], v[40:43]
	s_waitcnt lgkmcnt(0)
	v_mfma_f32_16x16x32_bf16 v[24:27], v[48:51], v[56:59], v[24:27]
	v_mfma_f32_16x16x32_bf16 v[28:31], v[48:51], v[64:67], v[28:31]
	v_mfma_f32_16x16x32_bf16 v[36:39], v[48:51], v[72:75], v[36:39]
	v_mfma_f32_16x16x32_bf16 v[40:43], v[48:51], v[80:83], v[40:43]
	s_waitcnt vmcnt(0)
	s_barrier
	ds_read_b128 v[88:91], v12
	ds_read_b128 v[96:99], v17 offset:0
	ds_read_b128 v[104:107], v17 offset:2048
	ds_read_b128 v[112:115], v17 offset:4096
	ds_read_b128 v[120:123], v17 offset:6144
	ds_read_b128 v[92:95], v144
	ds_read_b128 v[100:103], v149 offset:0
	ds_read_b128 v[108:111], v149 offset:2048
	ds_read_b128 v[116:119], v149 offset:4096
	ds_read_b128 v[124:127], v149 offset:6144
	s_waitcnt lgkmcnt(5)
	v_mfma_f32_16x16x32_bf16 v[24:27], v[88:91], v[96:99], v[24:27]
	v_mfma_f32_16x16x32_bf16 v[28:31], v[88:91], v[104:107], v[28:31]
	v_mfma_f32_16x16x32_bf16 v[36:39], v[88:91], v[112:115], v[36:39]
	v_mfma_f32_16x16x32_bf16 v[40:43], v[88:91], v[120:123], v[40:43]
	s_waitcnt lgkmcnt(0)
	v_mfma_f32_16x16x32_bf16 v[24:27], v[92:95], v[100:103], v[24:27]
	v_mfma_f32_16x16x32_bf16 v[28:31], v[92:95], v[108:111], v[28:31]
	v_mfma_f32_16x16x32_bf16 v[36:39], v[92:95], v[116:119], v[36:39]
	v_mfma_f32_16x16x32_bf16 v[40:43], v[92:95], v[124:127], v[40:43]
	s_barrier
	s_add_u32 s28, s6, 0xdb00000
	s_addc_u32 s29, s7, 0
	s_cmp_eq_u32 s36, 0
	s_cselect_b32 s28, s18, s28
	s_cselect_b32 s29, s19, s29
	s_cmp_eq_u32 s36, 1
	s_cselect_b32 s28, s20, s28
	s_cselect_b32 s29, s21, s29
	s_cmp_eq_u32 s36, 3
	s_cselect_b32 s28, s22, s28
	s_cselect_b32 s29, s23, s29
	s_lshl_b32 s33, s1, 11
	s_and_b32 s34, s35, 7
	s_lshl_b32 s34, s34, 8
	s_add_i32 s33, s33, s34
	s_add_u32 s28, s28, s33
	s_addc_u32 s29, s29, 0
	v_lshl_add_u64 v[136:137], s[28:29], 0, v[34:35]
	s_mov_b32 s30, 0x1000
	s_mov_b32 s31, 0
	v_lshl_add_u64 v[138:139], v[136:137], 0, s[30:31]
	s_cmp_eq_u32 s36, 2
	s_cbranch_scc1 .Lsg_hin_st
	s_cmp_eq_u32 s36, 1
	s_cbranch_scc1 .Lsg_hin_k
	v_mul_f32_e32 v140, 0xbfb8aa3b, v24
	v_mul_f32_e32 v141, 0xbfb8aa3b, v25
	v_mul_f32_e32 v142, 0xbfb8aa3b, v26
	v_mul_f32_e32 v143, 0xbfb8aa3b, v27
	v_exp_f32_e32 v140, v140
	v_exp_f32_e32 v141, v141
	v_exp_f32_e32 v142, v142
	v_exp_f32_e32 v143, v143
	v_add_f32_e32 v140, 1.0, v140
	v_add_f32_e32 v141, 1.0, v141
	v_add_f32_e32 v142, 1.0, v142
	v_add_f32_e32 v143, 1.0, v143
	v_rcp_f32_e32 v140, v140
	v_rcp_f32_e32 v141, v141
	v_rcp_f32_e32 v142, v142
	v_rcp_f32_e32 v143, v143
	v_mul_f32_e32 v24, v24, v140
	v_mul_f32_e32 v25, v25, v141
	v_mul_f32_e32 v26, v26, v142
	v_mul_f32_e32 v27, v27, v143
	v_mul_f32_e32 v140, 0xbfb8aa3b, v28
	v_mul_f32_e32 v141, 0xbfb8aa3b, v29
	v_mul_f32_e32 v142, 0xbfb8aa3b, v30
	v_mul_f32_e32 v143, 0xbfb8aa3b, v31
	v_exp_f32_e32 v140, v140
	v_exp_f32_e32 v141, v141
	v_exp_f32_e32 v142, v142
	v_exp_f32_e32 v143, v143
	v_add_f32_e32 v140, 1.0, v140
	v_add_f32_e32 v141, 1.0, v141
	v_add_f32_e32 v142, 1.0, v142
	v_add_f32_e32 v143, 1.0, v143
	v_rcp_f32_e32 v140, v140
	v_rcp_f32_e32 v141, v141
	v_rcp_f32_e32 v142, v142
	v_rcp_f32_e32 v143, v143
	v_mul_f32_e32 v28, v28, v140
	v_mul_f32_e32 v29, v29, v141
	v_mul_f32_e32 v30, v30, v142
	v_mul_f32_e32 v31, v31, v143
	v_mul_f32_e32 v140, 0xbfb8aa3b, v36
	v_mul_f32_e32 v141, 0xbfb8aa3b, v37
	v_mul_f32_e32 v142, 0xbfb8aa3b, v38
	v_mul_f32_e32 v143, 0xbfb8aa3b, v39
	v_exp_f32_e32 v140, v140
	v_exp_f32_e32 v141, v141
	v_exp_f32_e32 v142, v142
	v_exp_f32_e32 v143, v143
	v_add_f32_e32 v140, 1.0, v140
	v_add_f32_e32 v141, 1.0, v141
	v_add_f32_e32 v142, 1.0, v142
	v_add_f32_e32 v143, 1.0, v143
	v_rcp_f32_e32 v140, v140
	v_rcp_f32_e32 v141, v141
	v_rcp_f32_e32 v142, v142
	v_rcp_f32_e32 v143, v143
	v_mul_f32_e32 v36, v36, v140
	v_mul_f32_e32 v37, v37, v141
	v_mul_f32_e32 v38, v38, v142
	v_mul_f32_e32 v39, v39, v143
	v_mul_f32_e32 v140, 0xbfb8aa3b, v40
	v_mul_f32_e32 v141, 0xbfb8aa3b, v41
	v_mul_f32_e32 v142, 0xbfb8aa3b, v42
	v_mul_f32_e32 v143, 0xbfb8aa3b, v43
	v_exp_f32_e32 v140, v140
	v_exp_f32_e32 v141, v141
	v_exp_f32_e32 v142, v142
	v_exp_f32_e32 v143, v143
	v_add_f32_e32 v140, 1.0, v140
	v_add_f32_e32 v141, 1.0, v141
	v_add_f32_e32 v142, 1.0, v142
	v_add_f32_e32 v143, 1.0, v143
	v_rcp_f32_e32 v140, v140
	v_rcp_f32_e32 v141, v141
	v_rcp_f32_e32 v142, v142
	v_rcp_f32_e32 v143, v143
	v_mul_f32_e32 v40, v40, v140
	v_mul_f32_e32 v41, v41, v141
	v_mul_f32_e32 v42, v42, v142
	v_mul_f32_e32 v43, v43, v143
	s_cmp_eq_u32 s36, 0
	s_cbranch_scc0 .Lsg_hin_st
	v_mul_f32_e32 v24, 0x3db504f3, v24
	v_mul_f32_e32 v25, 0x3db504f3, v25
	v_mul_f32_e32 v26, 0x3db504f3, v26
	v_mul_f32_e32 v27, 0x3db504f3, v27
	v_mul_f32_e32 v28, 0x3db504f3, v28
	v_mul_f32_e32 v29, 0x3db504f3, v29
	v_mul_f32_e32 v30, 0x3db504f3, v30
	v_mul_f32_e32 v31, 0x3db504f3, v31
	v_mul_f32_e32 v36, 0x3db504f3, v36
	v_mul_f32_e32 v37, 0x3db504f3, v37
	v_mul_f32_e32 v38, 0x3db504f3, v38
	v_mul_f32_e32 v39, 0x3db504f3, v39
	v_mul_f32_e32 v40, 0x3db504f3, v40
	v_mul_f32_e32 v41, 0x3db504f3, v41
	v_mul_f32_e32 v42, 0x3db504f3, v42
	v_mul_f32_e32 v43, 0x3db504f3, v43
	s_branch .Lsg_hin_st

; #define LAS __attribute__((address_space(3)))
; template <class F>
; __device__ __forceinline__ void small_gemm_ks(LAS unsigned char* lds, const bf16_t* A, int lda, const bf16_t* Bt, int ldb, int K, int N, int a_grp_cols, int bx, int G, int tid, const F& f) {
;     const int lane = tid & 63, w = __builtin_amdgcn_readfirstlane(tid >> 6), c = lane & 15, g = lane >> 4, kh = w >> 2, wq = w & 3, wm = wq >> 1, wn = wq & 1;
;     const int ntn = N / 64, ntiles = (MS / 32) * ntn, KH = K / 2;
;     for (int t = bx; t < ntiles; t += G) {
;         const int row0 = MP + (t / ntn) * 32 + wm * 16, n0 = (t % ntn) * 64 + wn * 32;
;         const bf16_t* ap = A + (size_t)(row0 + c) * lda + (n0 >> 8) * a_grp_cols + kh * KH + 8 * g;
;         const bf16_t* bp = Bt + (size_t)(n0 + c) * ldb + kh * KH + 8 * g;
;         f32x4 acc[2] = {(f32x4){0.f, 0.f, 0.f, 0.f}, (f32x4){0.f, 0.f, 0.f, 0.f}};
; #pragma unroll 8
;         for (int k0 = 0; k0 < KH; k0 += 32) { const bf16x8 av = *(const bf16x8*)(ap + k0);
.LBB0_1988:
	s_waitcnt lgkmcnt(0)
	s_add_u32 s0, s6, 0x1d00000
	s_addc_u32 s1, s7, 0
	s_add_u32 s3, s6, 0x9900000
	s_addc_u32 s4, s7, 0
	s_add_u32 s10, s6, 0x5700000
	s_addc_u32 s11, s7, 0
	v_readfirstlane_b32 s6, v20
	s_and_b64 vcc, exec, s[88:89]
	v_and_b32_e32 v14, 15, v20
	s_cbranch_vccnz .LBB0_1995
	v_readfirstlane_b32 s68, v208
	v_and_b32_e32 v86, 63, v208
	s_nop 3
	s_lshr_b32 s68, s68, 6
	v_lshrrev_b32_e32 v87, 3, v86
	v_and_b32_e32 v88, 7, v86
	v_and_b32_e32 v94, 6, v87
	v_xor_b32_e32 v88, v88, v94
	s_mov_b32 s69, 5632
	v_mul_lo_u32 v90, v87, s69
	v_lshl_add_u32 v90, v88, 4, v90
	v_mov_b32_e32 v91, 0
	s_mov_b32 s69, 5632
	v_mul_lo_u32 v92, v87, s69
	v_lshl_add_u32 v92, v88, 4, v92
	v_mov_b32_e32 v93, 0
	v_and_b32_e32 v87, 15, v86
	v_lshrrev_b32_e32 v88, 4, v86
	v_lshrrev_b32_e32 v89, 3, v87
	v_lshlrev_b32_e32 v89, 10, v89
	v_and_b32_e32 v94, 6, v87
	v_xor_b32_e32 v94, v88, v94
	v_lshl_add_u32 v89, v94, 4, v89
	v_and_b32_e32 v94, 7, v87
	v_lshl_add_u32 v89, v94, 7, v89
	s_lshr_b32 s70, s68, 2
	s_bfe_u32 s71, s68, 0x10001
	s_and_b32 s72, s68, 1
	s_lshl_b32 s73, s70, 12
	s_lshl_b32 s74, s71, 11
	s_add_i32 s73, s73, s74
	s_lshl_b32 s74, s70, 13
	s_lshl_b32 s75, s72, 12
	s_add_i32 s74, s74, s75
	s_add_i32 s74, s74, 0x2000
	v_add_u32_e32 v96, s73, v89
	v_add_u32_e32 v101, s74, v89
	v_add_u32_e32 v97, s73, v89
	v_add_u32_e32 v102, s74, v89
	v_add_u32_e32 v98, s73, v89
	v_add_u32_e32 v103, s74, v89
	v_add_u32_e32 v99, s73, v89
	v_add_u32_e32 v104, s74, v89
	v_add_u32_e32 v100, s73, v89
	v_add_u32_e32 v105, s74, v89
	v_add_u32_e32 v97, 24576, v97
	v_add_u32_e32 v102, 24576, v102
	v_add_u32_e32 v98, 49152, v98
	v_add_u32_e32 v103, 49152, v103
	v_add_u32_e32 v99, 73728, v99
	v_add_u32_e32 v104, 73728, v104
	v_add_u32_e32 v100, 98304, v100
	v_add_u32_e32 v105, 98304, v105
	v_xor_b32_e32 v188, 64, v96
	v_xor_b32_e32 v193, 64, v101
	v_xor_b32_e32 v189, 64, v97
	v_xor_b32_e32 v194, 64, v102
	v_xor_b32_e32 v190, 64, v98
	v_xor_b32_e32 v195, 64, v103
	v_xor_b32_e32 v191, 64, v99
	v_xor_b32_e32 v196, 64, v104
	v_xor_b32_e32 v192, 64, v100
	v_xor_b32_e32 v197, 64, v105
	s_lshl_b32 s75, s71, 4
	v_lshl_add_u32 v106, v88, 2, s75
	v_lshlrev_b32_e32 v106, 11, v106
	s_lshl_b32 s75, s72, 5
	v_add_u32_e32 v107, s75, v87
	v_lshl_add_u32 v106, v107, 1, v106
	v_lshlrev_b32_e32 v108, 2, v107
	v_mov_b32_e32 v107, 0
	s_and_b32 s75, s68, 3
	s_lshl_b32 s75, s75, 11
	v_lshl_add_u32 v109, v86, 4, s75
	s_lshl_b32 s76, s68, 10
	s_lshl_b32 s77, s68, 11
	s_add_i32 s77, s77, 0x2000
	s_mov_b32 s78, 0x80
	s_mov_b32 s79, 0
	s_and_b32 s80, s68, 3
	s_mov_b32 s81, s2
.Lsg_dn1_tile:
	s_lshr_b32 s82, s81, 4
	s_and_b32 s83, s81, 15
	s_lshl_b32 s82, s82, 5
	s_add_i32 s82, s82, 0x4000
	s_lshl_b32 s83, s83, 6
	s_lshl_b32 s59, s80, 3
	s_add_i32 s59, s59, s82
	s_mul_i32 s60, s59, 5632
	s_mul_hi_u32 s61, s59, 5632
	s_mul_i32 s62, s70, 2816
	s_add_u32 s60, s60, s62
	s_addc_u32 s61, s61, 0
	s_add_u32 s60, s60, s54
	s_addc_u32 s61, s61, s55
	s_add_u32 s60, s60, 0x9900000
	s_addc_u32 s61, s61, 0
	v_lshl_add_u64 v[110:111], s[60:61], 0, v[90:91]
	s_lshl_b32 s59, s80, 4
	s_add_i32 s59, s59, s83
	s_mul_i32 s60, s59, 5632
	s_mul_i32 s62, s70, 2816
	s_add_u32 s60, s60, s62
	s_add_u32 s60, s60, s54
	s_addc_u32 s61, s55, 0
	s_add_u32 s60, s60, 0x1d00000
	s_addc_u32 s61, s61, 0
	v_lshl_add_u64 v[112:113], s[60:61], 0, v[92:93]
	s_add_u32 s60, s60, 45056
	s_addc_u32 s61, s61, 0
	v_lshl_add_u64 v[114:115], s[60:61], 0, v[92:93]
	s_waitcnt vmcnt(0)
	v_mov_b32_e32 v120, 0
	v_mov_b32_e32 v121, 0
	v_mov_b32_e32 v122, 0
	v_mov_b32_e32 v123, 0
	v_mov_b32_e32 v124, 0
	v_mov_b32_e32 v125, 0
	v_mov_b32_e32 v126, 0
	v_mov_b32_e32 v127, 0
	s_add_i32 m0, s76, 0
	s_nop 0
	global_load_lds_dwordx4 v[110:111], off
	v_lshl_add_u64 v[110:111], v[110:111], 0, s[78:79]
	s_add_i32 m0, s77, 0
	s_nop 0
	global_load_lds_dwordx4 v[112:113], off
	v_lshl_add_u64 v[112:113], v[112:113], 0, s[78:79]
	s_add_i32 m0, s77, 1024
	s_nop 0
	global_load_lds_dwordx4 v[114:115], off
	v_lshl_add_u64 v[114:115], v[114:115], 0, s[78:79]
	s_add_i32 m0, s76, 24576
	s_nop 0
	global_load_lds_dwordx4 v[110:111], off
	v_lshl_add_u64 v[110:111], v[110:111], 0, s[78:79]
	s_add_i32 m0, s77, 24576
	s_nop 0
	global_load_lds_dwordx4 v[112:113], off
	v_lshl_add_u64 v[112:113], v[112:113], 0, s[78:79]
	s_add_i32 m0, s77, 25600
	s_nop 0
	global_load_lds_dwordx4 v[114:115], off
	v_lshl_add_u64 v[114:115], v[114:115], 0, s[78:79]
	s_add_i32 m0, s76, 49152
	s_nop 0
	global_load_lds_dwordx4 v[110:111], off
	v_lshl_add_u64 v[110:111], v[110:111], 0, s[78:79]
	s_add_i32 m0, s77, 49152
	s_nop 0
	global_load_lds_dwordx4 v[112:113], off
	v_lshl_add_u64 v[112:113], v[112:113], 0, s[78:79]
	s_add_i32 m0, s77, 50176
	s_nop 0
	global_load_lds_dwordx4 v[114:115], off
	v_lshl_add_u64 v[114:115], v[114:115], 0, s[78:79]
	s_add_i32 m0, s76, 73728
	s_nop 0
	global_load_lds_dwordx4 v[110:111], off
	v_lshl_add_u64 v[110:111], v[110:111], 0, s[78:79]
	s_add_i32 m0, s77, 73728
	s_nop 0
	global_load_lds_dwordx4 v[112:113], off
	v_lshl_add_u64 v[112:113], v[112:113], 0, s[78:79]
	s_add_i32 m0, s77, 74752
	s_nop 0
	global_load_lds_dwordx4 v[114:115], off
	v_lshl_add_u64 v[114:115], v[114:115], 0, s[78:79]
	s_waitcnt vmcnt(9)
	s_barrier
; template <class F>
; __device__ __forceinline__ void small_gemm_ks(LAS unsigned char* lds, const bf16_t* A, int lda, const bf16_t* Bt, int ldb, int K, int N, int a_grp_cols, int bx, int G, int tid, const F& f) {
;     ...
; #pragma unroll 8
;         for (int k0 = 0; k0 < KH; k0 += 32) { const bf16x8 av = *(const bf16x8*)(ap + k0);
; #pragma unroll
;             for (int nt = 0; nt < 2; ++nt) { const bf16x8 bv = *(const bf16x8*)(bp + (size_t)nt * 16 * ldb + k0); acc[nt] = __builtin_amdgcn_mfma_f32_16x16x32_bf16(av, bv, acc[nt], 0, 0, 0); } }
	ds_read_b128 v[128:131], v96
	ds_read_b128 v[136:139], v101 offset:0
	ds_read_b128 v[144:147], v101 offset:2048
	ds_read_b128 v[132:135], v188
	ds_read_b128 v[140:143], v193 offset:0
	ds_read_b128 v[148:151], v193 offset:2048
	s_add_i32 m0, s76, 98304
	s_nop 0
	global_load_lds_dwordx4 v[110:111], off
	v_lshl_add_u64 v[110:111], v[110:111], 0, s[78:79]
	s_add_i32 m0, s77, 98304
	s_nop 0
	global_load_lds_dwordx4 v[112:113], off
	v_lshl_add_u64 v[112:113], v[112:113], 0, s[78:79]
	s_add_i32 m0, s77, 99328
	s_nop 0
	global_load_lds_dwordx4 v[114:115], off
	v_lshl_add_u64 v[114:115], v[114:115], 0, s[78:79]
	s_waitcnt lgkmcnt(3)
	v_mfma_f32_16x16x32_bf16 v[120:123], v[128:131], v[136:139], v[120:123]
	v_mfma_f32_16x16x32_bf16 v[124:127], v[128:131], v[144:147], v[124:127]
	s_waitcnt lgkmcnt(0)
	v_mfma_f32_16x16x32_bf16 v[120:123], v[132:135], v[140:143], v[120:123]
	v_mfma_f32_16x16x32_bf16 v[124:127], v[132:135], v[148:151], v[124:127]
	s_waitcnt vmcnt(9)
	s_barrier
	ds_read_b128 v[152:155], v97
	ds_read_b128 v[160:163], v102 offset:0
	ds_read_b128 v[168:171], v102 offset:2048
	ds_read_b128 v[156:159], v189
	ds_read_b128 v[164:167], v194 offset:0
	ds_read_b128 v[172:175], v194 offset:2048
	s_add_i32 m0, s76, 0
	s_nop 0
	global_load_lds_dwordx4 v[110:111], off
	v_lshl_add_u64 v[110:111], v[110:111], 0, s[78:79]
	s_add_i32 m0, s77, 0
	s_nop 0
	global_load_lds_dwordx4 v[112:113], off
	v_lshl_add_u64 v[112:113], v[112:113], 0, s[78:79]
	s_add_i32 m0, s77, 1024
	s_nop 0
	global_load_lds_dwordx4 v[114:115], off
	v_lshl_add_u64 v[114:115], v[114:115], 0, s[78:79]
	s_waitcnt lgkmcnt(3)
	v_mfma_f32_16x16x32_bf16 v[120:123], v[152:155], v[160:163], v[120:123]
	v_mfma_f32_16x16x32_bf16 v[124:127], v[152:155], v[168:171], v[124:127]
	s_waitcnt lgkmcnt(0)
	v_mfma_f32_16x16x32_bf16 v[120:123], v[156:159], v[164:167], v[120:123]
	v_mfma_f32_16x16x32_bf16 v[124:127], v[156:159], v[172:175], v[124:127]
	s_waitcnt vmcnt(9)
	s_barrier
	ds_read_b128 v[128:131], v98
	ds_read_b128 v[136:139], v103 offset:0
	ds_read_b128 v[144:147], v103 offset:2048
	ds_read_b128 v[132:135], v190
	ds_read_b128 v[140:143], v195 offset:0
	ds_read_b128 v[148:151], v195 offset:2048
	s_add_i32 m0, s76, 24576
	s_nop 0
	global_load_lds_dwordx4 v[110:111], off
	v_lshl_add_u64 v[110:111], v[110:111], 0, s[78:79]
	s_add_i32 m0, s77, 24576
	s_nop 0
	global_load_lds_dwordx4 v[112:113], off
	v_lshl_add_u64 v[112:113], v[112:113], 0, s[78:79]
	s_add_i32 m0, s77, 25600
	s_nop 0
	global_load_lds_dwordx4 v[114:115], off
	v_lshl_add_u64 v[114:115], v[114:115], 0, s[78:79]
	s_waitcnt lgkmcnt(3)
	v_mfma_f32_16x16x32_bf16 v[120:123], v[128:131], v[136:139], v[120:123]
	v_mfma_f32_16x16x32_bf16 v[124:127], v[128:131], v[144:147], v[124:127]
	s_waitcnt lgkmcnt(0)
	v_mfma_f32_16x16x32_bf16 v[120:123], v[132:135], v[140:143], v[120:123]
	v_mfma_f32_16x16x32_bf16 v[124:127], v[132:135], v[148:151], v[124:127]
	s_waitcnt vmcnt(9)
	s_barrier
	ds_read_b128 v[152:155], v99
	ds_read_b128 v[160:163], v104 offset:0
	ds_read_b128 v[168:171], v104 offset:2048
	ds_read_b128 v[156:159], v191
	ds_read_b128 v[164:167], v196 offset:0
	ds_read_b128 v[172:175], v196 offset:2048
	s_add_i32 m0, s76, 49152
	s_nop 0
	global_load_lds_dwordx4 v[110:111], off
	v_lshl_add_u64 v[110:111], v[110:111], 0, s[78:79]
	s_add_i32 m0, s77, 49152
	s_nop 0
	global_load_lds_dwordx4 v[112:113], off
	v_lshl_add_u64 v[112:113], v[112:113], 0, s[78:79]
	s_add_i32 m0, s77, 50176
	s_nop 0
	global_load_lds_dwordx4 v[114:115], off
	v_lshl_add_u64 v[114:115], v[114:115], 0, s[78:79]
	s_waitcnt lgkmcnt(3)
	v_mfma_f32_16x16x32_bf16 v[120:123], v[152:155], v[160:163], v[120:123]
	v_mfma_f32_16x16x32_bf16 v[124:127], v[152:155], v[168:171], v[124:127]
	s_waitcnt lgkmcnt(0)
	v_mfma_f32_16x16x32_bf16 v[120:123], v[156:159], v[164:167], v[120:123]
	v_mfma_f32_16x16x32_bf16 v[124:127], v[156:159], v[172:175], v[124:127]
	s_waitcnt vmcnt(9)
	s_barrier
	ds_read_b128 v[128:131], v100
	ds_read_b128 v[136:139], v105 offset:0
	ds_read_b128 v[144:147], v105 offset:2048
	ds_read_b128 v[132:135], v192
	ds_read_b128 v[140:143], v197 offset:0
	ds_read_b128 v[148:151], v197 offset:2048
	s_add_i32 m0, s76, 73728
	s_nop 0
	global_load_lds_dwordx4 v[110:111], off
	v_lshl_add_u64 v[110:111], v[110:111], 0, s[78:79]
	s_add_i32 m0, s77, 73728
	s_nop 0
	global_load_lds_dwordx4 v[112:113], off
	v_lshl_add_u64 v[112:113], v[112:113], 0, s[78:79]
	s_add_i32 m0, s77, 74752
	s_nop 0
	global_load_lds_dwordx4 v[114:115], off
	v_lshl_add_u64 v[114:115], v[114:115], 0, s[78:79]
	s_waitcnt lgkmcnt(3)
	v_mfma_f32_16x16x32_bf16 v[120:123], v[128:131], v[136:139], v[120:123]
	v_mfma_f32_16x16x32_bf16 v[124:127], v[128:131], v[144:147], v[124:127]
	s_waitcnt lgkmcnt(0)
	v_mfma_f32_16x16x32_bf16 v[120:123], v[132:135], v[140:143], v[120:123]
	v_mfma_f32_16x16x32_bf16 v[124:127], v[132:135], v[148:151], v[124:127]
	s_waitcnt vmcnt(9)
	s_barrier
	ds_read_b128 v[152:155], v96
	ds_read_b128 v[160:163], v101 offset:0
	ds_read_b128 v[168:171], v101 offset:2048
	ds_read_b128 v[156:159], v188
	ds_read_b128 v[164:167], v193 offset:0
	ds_read_b128 v[172:175], v193 offset:2048
	s_add_i32 m0, s76, 98304
	s_nop 0
	global_load_lds_dwordx4 v[110:111], off
	v_lshl_add_u64 v[110:111], v[110:111], 0, s[78:79]
	s_add_i32 m0, s77, 98304
	s_nop 0
	global_load_lds_dwordx4 v[112:113], off
	v_lshl_add_u64 v[112:113], v[112:113], 0, s[78:79]
	s_add_i32 m0, s77, 99328
	s_nop 0
	global_load_lds_dwordx4 v[114:115], off
	v_lshl_add_u64 v[114:115], v[114:115], 0, s[78:79]
	s_waitcnt lgkmcnt(3)
	v_mfma_f32_16x16x32_bf16 v[120:123], v[152:155], v[160:163], v[120:123]
	v_mfma_f32_16x16x32_bf16 v[124:127], v[152:155], v[168:171], v[124:127]
	s_waitcnt lgkmcnt(0)
	v_mfma_f32_16x16x32_bf16 v[120:123], v[156:159], v[164:167], v[120:123]
	v_mfma_f32_16x16x32_bf16 v[124:127], v[156:159], v[172:175], v[124:127]
	s_waitcnt vmcnt(9)
	s_barrier
; template <class F>
; __device__ __forceinline__ void small_gemm_ks(LAS unsigned char* lds, const bf16_t* A, int lda, const bf16_t* Bt, int ldb, int K, int N, int a_grp_cols, int bx, int G, int tid, const F& f) {
;     ...
; #pragma unroll 8
;         for (int k0 = 0; k0 < KH; k0 += 32) { const bf16x8 av = *(const bf16x8*)(ap + k0);
; #pragma unroll
;             for (int nt = 0; nt < 2; ++nt) { const bf16x8 bv = *(const bf16x8*)(bp + (size_t)nt * 16 * ldb + k0); acc[nt] = __builtin_amdgcn_mfma_f32_16x16x32_bf16(av, bv, acc[nt], 0, 0, 0); } }
	ds_read_b128 v[128:131], v97
	ds_read_b128 v[136:139], v102 offset:0
	ds_read_b128 v[144:147], v102 offset:2048
	ds_read_b128 v[132:135], v189
	ds_read_b128 v[140:143], v194 offset:0
	ds_read_b128 v[148:151], v194 offset:2048
	s_add_i32 m0, s76, 0
	s_nop 0
	global_load_lds_dwordx4 v[110:111], off
	v_lshl_add_u64 v[110:111], v[110:111], 0, s[78:79]
	s_add_i32 m0, s77, 0
	s_nop 0
	global_load_lds_dwordx4 v[112:113], off
	v_lshl_add_u64 v[112:113], v[112:113], 0, s[78:79]
	s_add_i32 m0, s77, 1024
	s_nop 0
	global_load_lds_dwordx4 v[114:115], off
	v_lshl_add_u64 v[114:115], v[114:115], 0, s[78:79]
	s_waitcnt lgkmcnt(3)
	v_mfma_f32_16x16x32_bf16 v[120:123], v[128:131], v[136:139], v[120:123]
	v_mfma_f32_16x16x32_bf16 v[124:127], v[128:131], v[144:147], v[124:127]
	s_waitcnt lgkmcnt(0)
	v_mfma_f32_16x16x32_bf16 v[120:123], v[132:135], v[140:143], v[120:123]
	v_mfma_f32_16x16x32_bf16 v[124:127], v[132:135], v[148:151], v[124:127]
	s_waitcnt vmcnt(9)
	s_barrier
	ds_read_b128 v[152:155], v98
	ds_read_b128 v[160:163], v103 offset:0
	ds_read_b128 v[168:171], v103 offset:2048
	ds_read_b128 v[156:159], v190
	ds_read_b128 v[164:167], v195 offset:0
	ds_read_b128 v[172:175], v195 offset:2048
	s_add_i32 m0, s76, 24576
	s_nop 0
	global_load_lds_dwordx4 v[110:111], off
	v_lshl_add_u64 v[110:111], v[110:111], 0, s[78:79]
	s_add_i32 m0, s77, 24576
	s_nop 0
	global_load_lds_dwordx4 v[112:113], off
	v_lshl_add_u64 v[112:113], v[112:113], 0, s[78:79]
	s_add_i32 m0, s77, 25600
	s_nop 0
	global_load_lds_dwordx4 v[114:115], off
	v_lshl_add_u64 v[114:115], v[114:115], 0, s[78:79]
	s_waitcnt lgkmcnt(3)
	v_mfma_f32_16x16x32_bf16 v[120:123], v[152:155], v[160:163], v[120:123]
	v_mfma_f32_16x16x32_bf16 v[124:127], v[152:155], v[168:171], v[124:127]
	s_waitcnt lgkmcnt(0)
	v_mfma_f32_16x16x32_bf16 v[120:123], v[156:159], v[164:167], v[120:123]
	v_mfma_f32_16x16x32_bf16 v[124:127], v[156:159], v[172:175], v[124:127]
	s_waitcnt vmcnt(9)
	s_barrier
	ds_read_b128 v[128:131], v99
	ds_read_b128 v[136:139], v104 offset:0
	ds_read_b128 v[144:147], v104 offset:2048
	ds_read_b128 v[132:135], v191
	ds_read_b128 v[140:143], v196 offset:0
	ds_read_b128 v[148:151], v196 offset:2048
	s_add_i32 m0, s76, 49152
	s_nop 0
	global_load_lds_dwordx4 v[110:111], off
	v_lshl_add_u64 v[110:111], v[110:111], 0, s[78:79]
	s_add_i32 m0, s77, 49152
	s_nop 0
	global_load_lds_dwordx4 v[112:113], off
	v_lshl_add_u64 v[112:113], v[112:113], 0, s[78:79]
	s_add_i32 m0, s77, 50176
	s_nop 0
	global_load_lds_dwordx4 v[114:115], off
	v_lshl_add_u64 v[114:115], v[114:115], 0, s[78:79]
	s_waitcnt lgkmcnt(3)
	v_mfma_f32_16x16x32_bf16 v[120:123], v[128:131], v[136:139], v[120:123]
	v_mfma_f32_16x16x32_bf16 v[124:127], v[128:131], v[144:147], v[124:127]
	s_waitcnt lgkmcnt(0)
	v_mfma_f32_16x16x32_bf16 v[120:123], v[132:135], v[140:143], v[120:123]
	v_mfma_f32_16x16x32_bf16 v[124:127], v[132:135], v[148:151], v[124:127]
	s_waitcnt vmcnt(9)
	s_barrier
	ds_read_b128 v[152:155], v100
	ds_read_b128 v[160:163], v105 offset:0
	ds_read_b128 v[168:171], v105 offset:2048
	ds_read_b128 v[156:159], v192
	ds_read_b128 v[164:167], v197 offset:0
	ds_read_b128 v[172:175], v197 offset:2048
	s_add_i32 m0, s76, 73728
	s_nop 0
	global_load_lds_dwordx4 v[110:111], off
	v_lshl_add_u64 v[110:111], v[110:111], 0, s[78:79]
	s_add_i32 m0, s77, 73728
	s_nop 0
	global_load_lds_dwordx4 v[112:113], off
	v_lshl_add_u64 v[112:113], v[112:113], 0, s[78:79]
	s_add_i32 m0, s77, 74752
	s_nop 0
	global_load_lds_dwordx4 v[114:115], off
	v_lshl_add_u64 v[114:115], v[114:115], 0, s[78:79]
	s_waitcnt lgkmcnt(3)
	v_mfma_f32_16x16x32_bf16 v[120:123], v[152:155], v[160:163], v[120:123]
	v_mfma_f32_16x16x32_bf16 v[124:127], v[152:155], v[168:171], v[124:127]
	s_waitcnt lgkmcnt(0)
	v_mfma_f32_16x16x32_bf16 v[120:123], v[156:159], v[164:167], v[120:123]
	v_mfma_f32_16x16x32_bf16 v[124:127], v[156:159], v[172:175], v[124:127]
	s_waitcnt vmcnt(9)
	s_barrier
	ds_read_b128 v[128:131], v96
	ds_read_b128 v[136:139], v101 offset:0
	ds_read_b128 v[144:147], v101 offset:2048
	ds_read_b128 v[132:135], v188
	ds_read_b128 v[140:143], v193 offset:0
	ds_read_b128 v[148:151], v193 offset:2048
	s_add_i32 m0, s76, 98304
	s_nop 0
	global_load_lds_dwordx4 v[110:111], off
	v_lshl_add_u64 v[110:111], v[110:111], 0, s[78:79]
	s_add_i32 m0, s77, 98304
	s_nop 0
	global_load_lds_dwordx4 v[112:113], off
	v_lshl_add_u64 v[112:113], v[112:113], 0, s[78:79]
	s_add_i32 m0, s77, 99328
	s_nop 0
	global_load_lds_dwordx4 v[114:115], off
	v_lshl_add_u64 v[114:115], v[114:115], 0, s[78:79]
	s_waitcnt lgkmcnt(3)
	v_mfma_f32_16x16x32_bf16 v[120:123], v[128:131], v[136:139], v[120:123]
	v_mfma_f32_16x16x32_bf16 v[124:127], v[128:131], v[144:147], v[124:127]
	s_waitcnt lgkmcnt(0)
	v_mfma_f32_16x16x32_bf16 v[120:123], v[132:135], v[140:143], v[120:123]
	v_mfma_f32_16x16x32_bf16 v[124:127], v[132:135], v[148:151], v[124:127]
	s_waitcnt vmcnt(9)
	s_barrier
	ds_read_b128 v[152:155], v97
	ds_read_b128 v[160:163], v102 offset:0
	ds_read_b128 v[168:171], v102 offset:2048
	ds_read_b128 v[156:159], v189
	ds_read_b128 v[164:167], v194 offset:0
	ds_read_b128 v[172:175], v194 offset:2048
	s_add_i32 m0, s76, 0
	s_nop 0
	global_load_lds_dwordx4 v[110:111], off
	v_lshl_add_u64 v[110:111], v[110:111], 0, s[78:79]
	s_add_i32 m0, s77, 0
	s_nop 0
	global_load_lds_dwordx4 v[112:113], off
	v_lshl_add_u64 v[112:113], v[112:113], 0, s[78:79]
	s_add_i32 m0, s77, 1024
	s_nop 0
	global_load_lds_dwordx4 v[114:115], off
	v_lshl_add_u64 v[114:115], v[114:115], 0, s[78:79]
	s_waitcnt lgkmcnt(3)
	v_mfma_f32_16x16x32_bf16 v[120:123], v[152:155], v[160:163], v[120:123]
	v_mfma_f32_16x16x32_bf16 v[124:127], v[152:155], v[168:171], v[124:127]
	s_waitcnt lgkmcnt(0)
	v_mfma_f32_16x16x32_bf16 v[120:123], v[156:159], v[164:167], v[120:123]
	v_mfma_f32_16x16x32_bf16 v[124:127], v[156:159], v[172:175], v[124:127]
	s_waitcnt vmcnt(9)
	s_barrier
; template <class F>
; __device__ __forceinline__ void small_gemm_ks(LAS unsigned char* lds, const bf16_t* A, int lda, const bf16_t* Bt, int ldb, int K, int N, int a_grp_cols, int bx, int G, int tid, const F& f) {
;     ...
; #pragma unroll 8
;         for (int k0 = 0; k0 < KH; k0 += 32) { const bf16x8 av = *(const bf16x8*)(ap + k0);
; #pragma unroll
;             for (int nt = 0; nt < 2; ++nt) { const bf16x8 bv = *(const bf16x8*)(bp + (size_t)nt * 16 * ldb + k0); acc[nt] = __builtin_amdgcn_mfma_f32_16x16x32_bf16(av, bv, acc[nt], 0, 0, 0); } }
	ds_read_b128 v[128:131], v98
	ds_read_b128 v[136:139], v103 offset:0
	ds_read_b128 v[144:147], v103 offset:2048
	ds_read_b128 v[132:135], v190
	ds_read_b128 v[140:143], v195 offset:0
	ds_read_b128 v[148:151], v195 offset:2048
	s_add_i32 m0, s76, 24576
	s_nop 0
	global_load_lds_dwordx4 v[110:111], off
	v_lshl_add_u64 v[110:111], v[110:111], 0, s[78:79]
	s_add_i32 m0, s77, 24576
	s_nop 0
	global_load_lds_dwordx4 v[112:113], off
	v_lshl_add_u64 v[112:113], v[112:113], 0, s[78:79]
	s_add_i32 m0, s77, 25600
	s_nop 0
	global_load_lds_dwordx4 v[114:115], off
	v_lshl_add_u64 v[114:115], v[114:115], 0, s[78:79]
	s_waitcnt lgkmcnt(3)
	v_mfma_f32_16x16x32_bf16 v[120:123], v[128:131], v[136:139], v[120:123]
	v_mfma_f32_16x16x32_bf16 v[124:127], v[128:131], v[144:147], v[124:127]
	s_waitcnt lgkmcnt(0)
	v_mfma_f32_16x16x32_bf16 v[120:123], v[132:135], v[140:143], v[120:123]
	v_mfma_f32_16x16x32_bf16 v[124:127], v[132:135], v[148:151], v[124:127]
	s_waitcnt vmcnt(9)
	s_barrier
	ds_read_b128 v[152:155], v99
	ds_read_b128 v[160:163], v104 offset:0
	ds_read_b128 v[168:171], v104 offset:2048
	ds_read_b128 v[156:159], v191
	ds_read_b128 v[164:167], v196 offset:0
	ds_read_b128 v[172:175], v196 offset:2048
	s_add_i32 m0, s76, 49152
	s_nop 0
	global_load_lds_dwordx4 v[110:111], off
	v_lshl_add_u64 v[110:111], v[110:111], 0, s[78:79]
	s_add_i32 m0, s77, 49152
	s_nop 0
	global_load_lds_dwordx4 v[112:113], off
	v_lshl_add_u64 v[112:113], v[112:113], 0, s[78:79]
	s_add_i32 m0, s77, 50176
	s_nop 0
	global_load_lds_dwordx4 v[114:115], off
	v_lshl_add_u64 v[114:115], v[114:115], 0, s[78:79]
	s_waitcnt lgkmcnt(3)
	v_mfma_f32_16x16x32_bf16 v[120:123], v[152:155], v[160:163], v[120:123]
	v_mfma_f32_16x16x32_bf16 v[124:127], v[152:155], v[168:171], v[124:127]
	s_waitcnt lgkmcnt(0)
	v_mfma_f32_16x16x32_bf16 v[120:123], v[156:159], v[164:167], v[120:123]
	v_mfma_f32_16x16x32_bf16 v[124:127], v[156:159], v[172:175], v[124:127]
	s_waitcnt vmcnt(9)
	s_barrier
	ds_read_b128 v[128:131], v100
	ds_read_b128 v[136:139], v105 offset:0
	ds_read_b128 v[144:147], v105 offset:2048
	ds_read_b128 v[132:135], v192
	ds_read_b128 v[140:143], v197 offset:0
	ds_read_b128 v[148:151], v197 offset:2048
	s_add_i32 m0, s76, 73728
	s_nop 0
	global_load_lds_dwordx4 v[110:111], off
	v_lshl_add_u64 v[110:111], v[110:111], 0, s[78:79]
	s_add_i32 m0, s77, 73728
	s_nop 0
	global_load_lds_dwordx4 v[112:113], off
	v_lshl_add_u64 v[112:113], v[112:113], 0, s[78:79]
	s_add_i32 m0, s77, 74752
	s_nop 0
	global_load_lds_dwordx4 v[114:115], off
	v_lshl_add_u64 v[114:115], v[114:115], 0, s[78:79]
	s_waitcnt lgkmcnt(3)
	v_mfma_f32_16x16x32_bf16 v[120:123], v[128:131], v[136:139], v[120:123]
	v_mfma_f32_16x16x32_bf16 v[124:127], v[128:131], v[144:147], v[124:127]
	s_waitcnt lgkmcnt(0)
	v_mfma_f32_16x16x32_bf16 v[120:123], v[132:135], v[140:143], v[120:123]
	v_mfma_f32_16x16x32_bf16 v[124:127], v[132:135], v[148:151], v[124:127]
	s_waitcnt vmcnt(9)
	s_barrier
	ds_read_b128 v[152:155], v96
	ds_read_b128 v[160:163], v101 offset:0
	ds_read_b128 v[168:171], v101 offset:2048
	ds_read_b128 v[156:159], v188
	ds_read_b128 v[164:167], v193 offset:0
	ds_read_b128 v[172:175], v193 offset:2048
	s_add_i32 m0, s76, 98304
	s_nop 0
	global_load_lds_dwordx4 v[110:111], off
	v_lshl_add_u64 v[110:111], v[110:111], 0, s[78:79]
	s_add_i32 m0, s77, 98304
	s_nop 0
	global_load_lds_dwordx4 v[112:113], off
	v_lshl_add_u64 v[112:113], v[112:113], 0, s[78:79]
	s_add_i32 m0, s77, 99328
	s_nop 0
	global_load_lds_dwordx4 v[114:115], off
	v_lshl_add_u64 v[114:115], v[114:115], 0, s[78:79]
	s_waitcnt lgkmcnt(3)
	v_mfma_f32_16x16x32_bf16 v[120:123], v[152:155], v[160:163], v[120:123]
	v_mfma_f32_16x16x32_bf16 v[124:127], v[152:155], v[168:171], v[124:127]
	s_waitcnt lgkmcnt(0)
	v_mfma_f32_16x16x32_bf16 v[120:123], v[156:159], v[164:167], v[120:123]
	v_mfma_f32_16x16x32_bf16 v[124:127], v[156:159], v[172:175], v[124:127]
	s_waitcnt vmcnt(9)
	s_barrier
; #define LAS __attribute__((address_space(3)))
; #define LDS_SYNC() do { asm volatile("s_waitcnt lgkmcnt(0)" ::: "memory"); __builtin_amdgcn_s_barrier(); asm volatile("" ::: "memory"); } while (0)
; template <class F>
; __device__ __forceinline__ void small_gemm_ks(LAS unsigned char* lds, const bf16_t* A, int lda, const bf16_t* Bt, int ldb, int K, int N, int a_grp_cols, int bx, int G, int tid, const F& f) {
;     ...
; #pragma unroll 8
;         for (int k0 = 0; k0 < KH; k0 += 32) { const bf16x8 av = *(const bf16x8*)(ap + k0);
; #pragma unroll
;             for (int nt = 0; nt < 2; ++nt) { const bf16x8 bv = *(const bf16x8*)(bp + (size_t)nt * 16 * ldb + k0); acc[nt] = __builtin_amdgcn_mfma_f32_16x16x32_bf16(av, bv, acc[nt], 0, 0, 0); } }
;         if (kh == 1) { *(LAS f32x4*)(lds + ((wq * 2 + 0) * 64 + lane) * 16) = acc[0]; *(LAS f32x4*)(lds + ((wq * 2 + 1) * 64 + lane) * 16) = acc[1]; }
;         LDS_SYNC();
	ds_read_b128 v[128:131], v97
	ds_read_b128 v[136:139], v102 offset:0
	ds_read_b128 v[144:147], v102 offset:2048
	ds_read_b128 v[132:135], v189
	ds_read_b128 v[140:143], v194 offset:0
	ds_read_b128 v[148:151], v194 offset:2048
	s_add_i32 m0, s76, 0
	s_nop 0
	global_load_lds_dwordx4 v[110:111], off
	v_lshl_add_u64 v[110:111], v[110:111], 0, s[78:79]
	s_add_i32 m0, s77, 0
	s_nop 0
	global_load_lds_dwordx4 v[112:113], off
	v_lshl_add_u64 v[112:113], v[112:113], 0, s[78:79]
	s_add_i32 m0, s77, 1024
	s_nop 0
	global_load_lds_dwordx4 v[114:115], off
	v_lshl_add_u64 v[114:115], v[114:115], 0, s[78:79]
	s_waitcnt lgkmcnt(3)
	v_mfma_f32_16x16x32_bf16 v[120:123], v[128:131], v[136:139], v[120:123]
	v_mfma_f32_16x16x32_bf16 v[124:127], v[128:131], v[144:147], v[124:127]
	s_waitcnt lgkmcnt(0)
	v_mfma_f32_16x16x32_bf16 v[120:123], v[132:135], v[140:143], v[120:123]
	v_mfma_f32_16x16x32_bf16 v[124:127], v[132:135], v[148:151], v[124:127]
	s_waitcnt vmcnt(9)
	s_barrier
	ds_read_b128 v[152:155], v98
	ds_read_b128 v[160:163], v103 offset:0
	ds_read_b128 v[168:171], v103 offset:2048
	ds_read_b128 v[156:159], v190
	ds_read_b128 v[164:167], v195 offset:0
	ds_read_b128 v[172:175], v195 offset:2048
	s_add_i32 m0, s76, 24576
	s_nop 0
	global_load_lds_dwordx4 v[110:111], off
	v_lshl_add_u64 v[110:111], v[110:111], 0, s[78:79]
	s_add_i32 m0, s77, 24576
	s_nop 0
	global_load_lds_dwordx4 v[112:113], off
	v_lshl_add_u64 v[112:113], v[112:113], 0, s[78:79]
	s_add_i32 m0, s77, 25600
	s_nop 0
	global_load_lds_dwordx4 v[114:115], off
	v_lshl_add_u64 v[114:115], v[114:115], 0, s[78:79]
	s_waitcnt lgkmcnt(3)
	v_mfma_f32_16x16x32_bf16 v[120:123], v[152:155], v[160:163], v[120:123]
	v_mfma_f32_16x16x32_bf16 v[124:127], v[152:155], v[168:171], v[124:127]
	s_waitcnt lgkmcnt(0)
	v_mfma_f32_16x16x32_bf16 v[120:123], v[156:159], v[164:167], v[120:123]
	v_mfma_f32_16x16x32_bf16 v[124:127], v[156:159], v[172:175], v[124:127]
	s_waitcnt vmcnt(9)
	s_barrier
	ds_read_b128 v[128:131], v99
	ds_read_b128 v[136:139], v104 offset:0
	ds_read_b128 v[144:147], v104 offset:2048
	ds_read_b128 v[132:135], v191
	ds_read_b128 v[140:143], v196 offset:0
	ds_read_b128 v[148:151], v196 offset:2048
	s_waitcnt lgkmcnt(3)
	v_mfma_f32_16x16x32_bf16 v[120:123], v[128:131], v[136:139], v[120:123]
	v_mfma_f32_16x16x32_bf16 v[124:127], v[128:131], v[144:147], v[124:127]
	s_waitcnt lgkmcnt(0)
	v_mfma_f32_16x16x32_bf16 v[120:123], v[132:135], v[140:143], v[120:123]
	v_mfma_f32_16x16x32_bf16 v[124:127], v[132:135], v[148:151], v[124:127]
	s_waitcnt vmcnt(6)
	s_barrier
	ds_read_b128 v[152:155], v100
	ds_read_b128 v[160:163], v105 offset:0
	ds_read_b128 v[168:171], v105 offset:2048
	ds_read_b128 v[156:159], v192
	ds_read_b128 v[164:167], v197 offset:0
	ds_read_b128 v[172:175], v197 offset:2048
	s_waitcnt lgkmcnt(3)
	v_mfma_f32_16x16x32_bf16 v[120:123], v[152:155], v[160:163], v[120:123]
	v_mfma_f32_16x16x32_bf16 v[124:127], v[152:155], v[168:171], v[124:127]
	s_waitcnt lgkmcnt(0)
	v_mfma_f32_16x16x32_bf16 v[120:123], v[156:159], v[164:167], v[120:123]
	v_mfma_f32_16x16x32_bf16 v[124:127], v[156:159], v[172:175], v[124:127]
	s_waitcnt vmcnt(3)
	s_barrier
	ds_read_b128 v[128:131], v96
	ds_read_b128 v[136:139], v101 offset:0
	ds_read_b128 v[144:147], v101 offset:2048
	ds_read_b128 v[132:135], v188
	ds_read_b128 v[140:143], v193 offset:0
	ds_read_b128 v[148:151], v193 offset:2048
	s_waitcnt lgkmcnt(3)
	v_mfma_f32_16x16x32_bf16 v[120:123], v[128:131], v[136:139], v[120:123]
	v_mfma_f32_16x16x32_bf16 v[124:127], v[128:131], v[144:147], v[124:127]
	s_waitcnt lgkmcnt(0)
	v_mfma_f32_16x16x32_bf16 v[120:123], v[132:135], v[140:143], v[120:123]
	v_mfma_f32_16x16x32_bf16 v[124:127], v[132:135], v[148:151], v[124:127]
	s_waitcnt vmcnt(0)
	s_barrier
	ds_read_b128 v[152:155], v97
	ds_read_b128 v[160:163], v102 offset:0
	ds_read_b128 v[168:171], v102 offset:2048
	ds_read_b128 v[156:159], v189
	ds_read_b128 v[164:167], v194 offset:0
	ds_read_b128 v[172:175], v194 offset:2048
	s_waitcnt lgkmcnt(3)
	v_mfma_f32_16x16x32_bf16 v[120:123], v[152:155], v[160:163], v[120:123]
	v_mfma_f32_16x16x32_bf16 v[124:127], v[152:155], v[168:171], v[124:127]
	s_waitcnt lgkmcnt(0)
	v_mfma_f32_16x16x32_bf16 v[120:123], v[156:159], v[164:167], v[120:123]
	v_mfma_f32_16x16x32_bf16 v[124:127], v[156:159], v[172:175], v[124:127]
	s_barrier
	s_lshl_b32 s59, s82, 11
	s_lshl_b32 s62, s83, 1
	s_add_i32 s59, s59, s62
	s_add_u32 s60, s54, s59
	s_addc_u32 s61, s55, 0
	s_add_u32 s60, s60, 0x5700000
	s_addc_u32 s61, s61, 0
	v_lshl_add_u64 v[176:177], s[60:61], 0, v[106:107]
	s_mov_b32 s62, 0x1000
	s_mov_b32 s63, 0
	v_lshl_add_u64 v[178:179], v[176:177], 0, s[62:63]
	s_cmp_eq_u32 s70, 0
	s_cbranch_scc1 .Lsg_dn1_lo
	s_nop 4
	ds_write_b128 v109, v[120:123]
	ds_write_b128 v109, v[124:127] offset:1024
	s_waitcnt lgkmcnt(0)
	s_barrier
	s_branch .Lsg_dn1_done
